# score R-merge: compare-exchange insertion chains replaced by per-position v_med3_f32 updates (half the VALU ops)
# speedup vs baseline: 1.0137x; 1.0026x over previous
; DEV f32x4 mfma16(bf16x8 a, bf16x8 b, f32x4 c) { return __builtin_amdgcn_mfma_f32_16x16x32_bf16(a, b, c, 0, 0, 0); }
; DEV void peer_top16(const bf16_t* __restrict__ pq, const bf16_t* sk  , float (&l)[16]) {
;     ...
; #pragma unroll 1
;   for (int ks = 0; ks < 4; ks++) {
;     const bf16x8 bqk = *(const bf16x8*)(pq + ks * 32 + quad * 8);
; #pragma unroll
;     for (int nt = 0; nt < 8; nt++) {
;       bf16x8 ak = *(const bf16x8*)(sk + (nt * 16 + l15) * 144 + ks * 32 + quad * 8);
;       acc[nt] = mfma16(ak, bqk, acc[nt]);
;     }
;   }
.LBB0_170:
	v_add_u32_e32 v139, 0x10e00, v122
	ds_read_b128 v[164:167], v122 offset:36864
	ds_read_b128 v[168:171], v122 offset:41472
	ds_read_b128 v[172:175], v122 offset:46080
	ds_read_b128 v[176:179], v122 offset:50688
	ds_read_b128 v[180:183], v122 offset:55296
	ds_read_b128 v[184:187], v122 offset:59904
	ds_read_b128 v[188:191], v122 offset:64512
	ds_read_b128 v[128:131], v139
	s_waitcnt vmcnt(3) lgkmcnt(7)
	v_mfma_f32_16x16x32_bf16 v[30:33], v[164:167], v[148:151], v[30:33]
	ds_read_b128 v[164:167], v122 offset:36928
	s_waitcnt lgkmcnt(7)
	v_mfma_f32_16x16x32_bf16 v[22:25], v[168:171], v[148:151], v[22:25]
	ds_read_b128 v[168:171], v122 offset:41536
	s_waitcnt lgkmcnt(7)
	v_mfma_f32_16x16x32_bf16 v[14:17], v[172:175], v[148:151], v[14:17]
	ds_read_b128 v[172:175], v122 offset:46144
	s_waitcnt lgkmcnt(7)
	v_mfma_f32_16x16x32_bf16 v[6:9], v[176:179], v[148:151], v[6:9]
	ds_read_b128 v[176:179], v122 offset:50752
	s_waitcnt lgkmcnt(7)
	v_mfma_f32_16x16x32_bf16 v[26:29], v[180:183], v[148:151], v[26:29]
	ds_read_b128 v[180:183], v122 offset:55360
	s_waitcnt lgkmcnt(7)
	v_mfma_f32_16x16x32_bf16 v[18:21], v[184:187], v[148:151], v[18:21]
	ds_read_b128 v[184:187], v122 offset:59968
	s_waitcnt lgkmcnt(7)
	v_mfma_f32_16x16x32_bf16 v[10:13], v[188:191], v[148:151], v[10:13]
	ds_read_b128 v[188:191], v122 offset:64576
	s_waitcnt lgkmcnt(7)
	v_mfma_f32_16x16x32_bf16 v[2:5], v[128:131], v[148:151], v[2:5]
	ds_read_b128 v[128:131], v139 offset:64
	s_waitcnt vmcnt(2) lgkmcnt(7)
	v_mfma_f32_16x16x32_bf16 v[30:33], v[164:167], v[152:155], v[30:33]
	ds_read_b128 v[164:167], v122 offset:36992
	s_waitcnt lgkmcnt(7)
	v_mfma_f32_16x16x32_bf16 v[22:25], v[168:171], v[152:155], v[22:25]
	ds_read_b128 v[168:171], v122 offset:41600
	s_waitcnt lgkmcnt(7)
	v_mfma_f32_16x16x32_bf16 v[14:17], v[172:175], v[152:155], v[14:17]
	ds_read_b128 v[172:175], v122 offset:46208
	s_waitcnt lgkmcnt(7)
	v_mfma_f32_16x16x32_bf16 v[6:9], v[176:179], v[152:155], v[6:9]
	ds_read_b128 v[176:179], v122 offset:50816
	s_waitcnt lgkmcnt(7)
	v_mfma_f32_16x16x32_bf16 v[26:29], v[180:183], v[152:155], v[26:29]
	ds_read_b128 v[180:183], v122 offset:55424
	s_waitcnt lgkmcnt(7)
	v_mfma_f32_16x16x32_bf16 v[18:21], v[184:187], v[152:155], v[18:21]
	ds_read_b128 v[184:187], v122 offset:60032
	s_waitcnt lgkmcnt(7)
	v_mfma_f32_16x16x32_bf16 v[10:13], v[188:191], v[152:155], v[10:13]
	ds_read_b128 v[188:191], v122 offset:64640
	s_waitcnt lgkmcnt(7)
	v_mfma_f32_16x16x32_bf16 v[2:5], v[128:131], v[152:155], v[2:5]
	ds_read_b128 v[128:131], v139 offset:128
	s_waitcnt vmcnt(1) lgkmcnt(7)
	v_mfma_f32_16x16x32_bf16 v[30:33], v[164:167], v[156:159], v[30:33]
	ds_read_b128 v[164:167], v122 offset:37056
	s_waitcnt lgkmcnt(7)
	v_mfma_f32_16x16x32_bf16 v[22:25], v[168:171], v[156:159], v[22:25]
	ds_read_b128 v[168:171], v122 offset:41664
	s_waitcnt lgkmcnt(7)
	v_mfma_f32_16x16x32_bf16 v[14:17], v[172:175], v[156:159], v[14:17]
	ds_read_b128 v[172:175], v122 offset:46272
	s_waitcnt lgkmcnt(7)
	v_mfma_f32_16x16x32_bf16 v[6:9], v[176:179], v[156:159], v[6:9]
	ds_read_b128 v[176:179], v122 offset:50880
	s_waitcnt lgkmcnt(7)
	v_mfma_f32_16x16x32_bf16 v[26:29], v[180:183], v[156:159], v[26:29]
	ds_read_b128 v[180:183], v122 offset:55488
	s_waitcnt lgkmcnt(7)
	v_mfma_f32_16x16x32_bf16 v[18:21], v[184:187], v[156:159], v[18:21]
	ds_read_b128 v[184:187], v122 offset:60096
	s_waitcnt lgkmcnt(7)
	v_mfma_f32_16x16x32_bf16 v[10:13], v[188:191], v[156:159], v[10:13]
	ds_read_b128 v[188:191], v122 offset:64704
	s_waitcnt lgkmcnt(7)
	v_mfma_f32_16x16x32_bf16 v[2:5], v[128:131], v[156:159], v[2:5]
	ds_read_b128 v[128:131], v139 offset:192
	s_waitcnt vmcnt(0) lgkmcnt(7)
	v_mfma_f32_16x16x32_bf16 v[30:33], v[164:167], v[160:163], v[30:33]
	s_waitcnt lgkmcnt(6)
	v_mfma_f32_16x16x32_bf16 v[22:25], v[168:171], v[160:163], v[22:25]
	s_waitcnt lgkmcnt(5)
	v_mfma_f32_16x16x32_bf16 v[14:17], v[172:175], v[160:163], v[14:17]
	s_waitcnt lgkmcnt(4)
	v_mfma_f32_16x16x32_bf16 v[6:9], v[176:179], v[160:163], v[6:9]
	s_waitcnt lgkmcnt(3)
	v_mfma_f32_16x16x32_bf16 v[26:29], v[180:183], v[160:163], v[26:29]
	s_waitcnt lgkmcnt(2)
	v_mfma_f32_16x16x32_bf16 v[18:21], v[184:187], v[160:163], v[18:21]
	s_waitcnt lgkmcnt(1)
	v_mfma_f32_16x16x32_bf16 v[10:13], v[188:191], v[160:163], v[10:13]
	s_waitcnt lgkmcnt(0)
; DEV void peer_top16(const bf16_t* __restrict__ pq, const bf16_t* sk  , float (&l)[16]) {
;     ...
;   float hi[16];
; #pragma unroll
;   for (int nt = 0; nt < 4; nt++)
; #pragma unroll
;     for (int r = 0; r < 4; r++) {
;       l[nt * 4 + r] = __uint_as_float((__float_as_uint(acc[nt][r]) & ~127u) | (unsigned)(nt * 16 + quad * 4 + r));
;       hi[nt * 4 + r] = __uint_as_float((__float_as_uint(acc[nt + 4][r]) & ~127u) | (unsigned)((nt + 4) * 16 + quad * 4 + r));
;     }
;   sort16_desc(l);
;   sort16_desc(hi);
; #pragma unroll
;   for (int i = 0; i < 16; i++) l[i] = fmaxf(l[i], hi[15 - i]);
;   bitonic16(l);
	v_mfma_f32_16x16x32_bf16 v[2:5], v[128:131], v[160:163], v[2:5]
	s_movk_i32 s0, 0x100
	v_max_f32_e32 v0, v109, v121
	v_max_f32_e32 v100, v107, v120
	v_max_f32_e32 v101, v105, v119
	v_max_f32_e32 v103, v103, v118
	v_max_f32_e32 v87, v87, v116
	v_max_f32_e32 v79, v79, v115
	v_max_f32_e32 v75, v75, v114
	v_max_f32_e32 v71, v71, v113
	v_max_f32_e32 v67, v67, v112
	v_max_f32_e32 v63, v63, v111
	v_max_f32_e32 v59, v59, v110
	v_max_f32_e32 v55, v55, v108
	v_max_f32_e32 v51, v51, v106
	v_max_f32_e32 v47, v47, v104
	v_max_f32_e32 v43, v43, v91
	v_max_f32_e32 v39, v39, v83
	v_max_f32_e32 v83, v0, v67
	v_min_f32_e32 v0, v0, v67
	v_max_f32_e32 v67, v100, v63
	v_min_f32_e32 v63, v100, v63
	v_max_f32_e32 v91, v101, v59
	v_min_f32_e32 v59, v101, v59
	v_max_f32_e32 v100, v103, v55
	v_min_f32_e32 v55, v103, v55
	v_max_f32_e32 v101, v87, v51
	v_min_f32_e32 v51, v87, v51
	v_max_f32_e32 v87, v79, v47
	v_min_f32_e32 v47, v79, v47
	v_max_f32_e32 v79, v75, v43
	v_min_f32_e32 v43, v75, v43
	v_max_f32_e32 v75, v71, v39
	v_min_f32_e32 v39, v71, v39
	v_max_f32_e32 v71, v83, v101
	v_min_f32_e32 v101, v83, v101
	v_max_f32_e32 v103, v67, v87
	v_min_f32_e32 v67, v67, v87
	v_max_f32_e32 v87, v91, v79
	v_min_f32_e32 v79, v91, v79
	v_max_f32_e32 v91, v100, v75
	v_min_f32_e32 v75, v100, v75
	v_max_f32_e32 v100, v0, v51
	v_min_f32_e32 v0, v0, v51
	v_max_f32_e32 v51, v63, v47
	v_max_f32_e32 v105, v59, v43
	v_min_f32_e32 v43, v59, v43
	v_max_f32_e32 v59, v55, v39
	v_min_f32_e32 v107, v101, v79
	v_min_f32_e32 v108, v67, v75
	v_min_f32_e32 v110, v51, v59
	v_max_f32_e32 v79, v101, v79
	v_max_f32_e32 v67, v67, v75
	v_max_f32_e32 v101, v100, v105
	v_max_f32_e32 v51, v51, v59
	v_min_f32_e32 v75, v79, v67
	v_min_f32_e32 v59, v101, v51
	v_max_f32_e32 v79, v79, v67
	v_max_f32_e32 v67, v101, v51
	v_lshlrev_b32_e32 v101, 2, v102
	s_movk_i32 s0, 0xff80
	v_and_or_b32 v30, v30, s0, v101
	v_and_b32_e32 v27, 0xffffff80, v27
	s_movk_i32 s0, 0x41
	v_or3_b32 v27, v101, v27, s0
	v_and_b32_e32 v28, 0xffffff80, v28
	s_movk_i32 s0, 0x42
	v_or3_b32 v28, v101, v28, s0
	v_and_b32_e32 v29, 0xffffff80, v29
	s_movk_i32 s0, 0x43
	v_or3_b32 v29, v101, v29, s0
	v_and_b32_e32 v18, 0xffffff80, v18
	s_movk_i32 s0, 0x50
	v_or3_b32 v18, v101, v18, s0
	v_and_b32_e32 v19, 0xffffff80, v19
	s_movk_i32 s0, 0x51
	v_or3_b32 v19, v101, v19, s0
	v_and_b32_e32 v20, 0xffffff80, v20
	s_movk_i32 s0, 0x52
	v_or3_b32 v20, v101, v20, s0
	v_and_b32_e32 v21, 0xffffff80, v21
	s_movk_i32 s0, 0x53
	v_or3_b32 v21, v101, v21, s0
	v_and_b32_e32 v10, 0xffffff80, v10
	s_movk_i32 s0, 0x60
	v_or3_b32 v10, v101, v10, s0
	v_and_b32_e32 v11, 0xffffff80, v11
	s_movk_i32 s0, 0x61
	v_or3_b32 v11, v101, v11, s0
	v_and_b32_e32 v12, 0xffffff80, v12
	s_movk_i32 s0, 0x62
	v_or3_b32 v12, v101, v12, s0
	v_and_b32_e32 v13, 0xffffff80, v13
	s_movk_i32 s0, 0x63
	v_or3_b32 v13, v101, v13, s0
	v_and_b32_e32 v2, 0xffffff80, v2
	s_movk_i32 s0, 0x70
	v_and_b32_e32 v26, 0xffffff80, v26
	v_and_b32_e32 v31, 0xffffff80, v31
	v_or3_b32 v2, v101, v2, s0
	v_and_b32_e32 v3, 0xffffff80, v3
	s_movk_i32 s0, 0x71
	v_or3_b32 v26, v101, v26, 64
	v_or3_b32 v31, v101, v31, 1
	v_and_b32_e32 v32, 0xffffff80, v32
	v_and_b32_e32 v33, 0xffffff80, v33
	v_and_b32_e32 v22, 0xffffff80, v22
	v_and_b32_e32 v23, 0xffffff80, v23
	v_or3_b32 v3, v101, v3, s0
	v_and_b32_e32 v4, 0xffffff80, v4
	s_movk_i32 s0, 0x72
	v_min_f32_e32 v39, v55, v39
	v_min_f32_e32 v55, v71, v87
	v_min_f32_e32 v106, v103, v91
	v_min_f32_e32 v109, v100, v105
	v_max_f32_e32 v71, v71, v87
	v_max_f32_e32 v87, v103, v91
	v_or3_b32 v32, v101, v32, 2
	v_or3_b32 v33, v101, v33, 3
	v_or3_b32 v22, v101, v22, 16
	v_or3_b32 v23, v101, v23, 17
	v_and_b32_e32 v24, 0xffffff80, v24
	v_and_b32_e32 v25, 0xffffff80, v25
	v_and_b32_e32 v14, 0xffffff80, v14
	v_and_b32_e32 v15, 0xffffff80, v15
	v_and_b32_e32 v16, 0xffffff80, v16
	v_and_b32_e32 v17, 0xffffff80, v17
	v_and_b32_e32 v6, 0xffffff80, v6
	v_and_b32_e32 v7, 0xffffff80, v7
	v_and_b32_e32 v8, 0xffffff80, v8
	v_or3_b32 v4, v101, v4, s0
	v_and_b32_e32 v9, 0xffffff80, v9
	v_and_b32_e32 v5, 0xffffff80, v5
	s_movk_i32 s0, 0x73
	v_min_f32_e32 v104, v63, v47
	v_min_f32_e32 v83, v55, v106
	v_min_f32_e32 v47, v109, v110
	v_min_f32_e32 v91, v71, v87
	v_max_f32_e32 v100, v71, v87
	v_max_f32_e32 v87, v55, v106
	v_max_f32_e32 v55, v109, v110
	v_or3_b32 v24, v101, v24, 18
	v_or3_b32 v25, v101, v25, 19
	v_or3_b32 v14, v101, v14, 32
	v_or3_b32 v15, v101, v15, 33
	v_or3_b32 v16, v101, v16, 34
	v_or3_b32 v17, v101, v17, 35
	v_or3_b32 v6, v101, v6, 48
	v_or3_b32 v7, v101, v7, 49
	v_or3_b32 v8, v101, v8, 50
	v_or3_b32 v9, v101, v9, 51
	v_or3_b32 v5, v101, v5, s0
	v_max_f32_e32 v101, v30, v31
	v_min_f32_e32 v30, v30, v31
	v_max_f32_e32 v31, v32, v32
	v_max_f32_e32 v32, v33, v33
	v_max_f32_e32 v109, v26, v27
	v_min_f32_e32 v26, v26, v27
	v_max_f32_e32 v27, v28, v28
	v_max_f32_e32 v28, v29, v29
	v_max_f32_e32 v33, v32, v31
	v_min_f32_e32 v31, v32, v31
	v_max_f32_e32 v32, v22, v23
	v_min_f32_e32 v22, v22, v23
	v_max_f32_e32 v23, v24, v24
	v_max_f32_e32 v24, v25, v25
	v_max_f32_e32 v29, v28, v27
	v_min_f32_e32 v27, v28, v27
	v_max_f32_e32 v28, v18, v19
	v_min_f32_e32 v18, v18, v19
	v_max_f32_e32 v19, v20, v20
	v_max_f32_e32 v20, v21, v21
	v_max_f32_e32 v25, v24, v23
	v_min_f32_e32 v23, v24, v23
	v_max_f32_e32 v24, v14, v15
	v_min_f32_e32 v14, v14, v15
	v_max_f32_e32 v15, v16, v16
	v_max_f32_e32 v16, v17, v17
	v_max_f32_e32 v21, v20, v19
	v_min_f32_e32 v19, v20, v19
	v_max_f32_e32 v20, v10, v11
	v_min_f32_e32 v10, v10, v11
	v_max_f32_e32 v11, v12, v12
	v_max_f32_e32 v12, v13, v13
	v_max_f32_e32 v17, v16, v15
	v_min_f32_e32 v15, v16, v15
	v_max_f32_e32 v16, v6, v7
	v_min_f32_e32 v6, v6, v7
; DEV void ce(float& a, float& b) { float hi = fmaxf(a, b), lo = fminf(a, b); a = hi; b = lo; }
; DEV void sort16_desc(float (&a)[16]) {
; #pragma unroll
;   for (int k = 2; k <= 16; k <<= 1)
; #pragma unroll
;     for (int j = k >> 1; j > 0; j >>= 1)
; #pragma unroll
;       for (int i = 0; i < 16; i++) {
;         const int p = i ^ j;
;         if (p > i) { if ((i & k) == 0) ce(a[i], a[p]); else ce(a[p], a[i]); }
;       }
; }
	v_max_f32_e32 v7, v8, v8
	v_max_f32_e32 v8, v9, v9
	v_max_f32_e32 v13, v12, v11
	v_min_f32_e32 v11, v12, v11
	v_max_f32_e32 v12, v2, v3
	v_min_f32_e32 v2, v2, v3
	v_max_f32_e32 v3, v4, v4
	v_max_f32_e32 v4, v5, v5
	v_max_f32_e32 v9, v8, v7
	v_min_f32_e32 v7, v8, v7
	v_max_f32_e32 v5, v4, v3
	v_min_f32_e32 v3, v4, v3
	v_max_f32_e32 v8, v101, v31
	v_min_f32_e32 v31, v101, v31
	v_max_f32_e32 v101, v30, v33
	v_min_f32_e32 v30, v30, v33
	v_max_f32_e32 v33, v23, v32
	v_min_f32_e32 v23, v23, v32
	v_max_f32_e32 v32, v25, v22
	v_min_f32_e32 v22, v25, v22
	v_max_f32_e32 v25, v24, v15
	v_min_f32_e32 v15, v24, v15
	v_max_f32_e32 v24, v14, v17
	v_min_f32_e32 v14, v14, v17
	v_max_f32_e32 v17, v7, v16
	v_min_f32_e32 v7, v7, v16
	v_max_f32_e32 v16, v9, v6
	v_min_f32_e32 v6, v9, v6
	v_max_f32_e32 v4, v109, v27
	v_min_f32_e32 v27, v109, v27
	v_max_f32_e32 v109, v26, v29
	v_min_f32_e32 v26, v26, v29
	v_max_f32_e32 v29, v19, v28
	v_min_f32_e32 v19, v19, v28
	v_max_f32_e32 v28, v21, v18
	v_min_f32_e32 v18, v21, v18
	v_max_f32_e32 v21, v20, v11
	v_min_f32_e32 v11, v20, v11
	v_max_f32_e32 v20, v10, v13
	v_min_f32_e32 v10, v10, v13
	v_max_f32_e32 v13, v3, v12
	v_min_f32_e32 v3, v3, v12
	v_max_f32_e32 v12, v5, v2
	v_min_f32_e32 v2, v5, v2
	v_max_f32_e32 v9, v8, v101
	v_min_f32_e32 v8, v8, v101
	v_max_f32_e32 v101, v31, v30
	v_min_f32_e32 v30, v31, v30
	v_max_f32_e32 v31, v22, v23
	v_min_f32_e32 v22, v22, v23
	v_max_f32_e32 v23, v32, v33
	v_min_f32_e32 v32, v32, v33
	v_max_f32_e32 v33, v25, v24
	v_min_f32_e32 v24, v25, v24
	v_max_f32_e32 v25, v15, v14
	v_min_f32_e32 v14, v15, v14
	v_max_f32_e32 v15, v6, v7
	v_min_f32_e32 v6, v6, v7
	v_max_f32_e32 v7, v16, v17
	v_min_f32_e32 v16, v16, v17
	v_max_f32_e32 v5, v4, v109
	v_min_f32_e32 v4, v4, v109
	v_max_f32_e32 v109, v27, v26
	v_min_f32_e32 v26, v27, v26
	v_max_f32_e32 v27, v18, v19
	v_min_f32_e32 v18, v18, v19
	v_max_f32_e32 v19, v28, v29
	v_min_f32_e32 v28, v28, v29
	v_max_f32_e32 v29, v21, v20
	v_min_f32_e32 v20, v21, v20
	v_max_f32_e32 v21, v11, v10
	v_min_f32_e32 v10, v11, v10
	v_max_f32_e32 v11, v2, v3
	v_min_f32_e32 v2, v2, v3
	v_max_f32_e32 v3, v12, v13
	v_min_f32_e32 v12, v12, v13
	v_max_f32_e32 v17, v9, v22
	v_min_f32_e32 v9, v9, v22
	v_max_f32_e32 v22, v8, v31
	v_min_f32_e32 v8, v8, v31
	v_max_f32_e32 v31, v101, v32
	v_min_f32_e32 v32, v101, v32
	v_max_f32_e32 v101, v30, v23
	v_min_f32_e32 v23, v30, v23
	v_max_f32_e32 v30, v6, v33
	v_min_f32_e32 v6, v6, v33
	v_max_f32_e32 v33, v15, v24
	v_min_f32_e32 v15, v15, v24
	v_max_f32_e32 v24, v16, v25
	v_min_f32_e32 v16, v16, v25
	v_max_f32_e32 v25, v7, v14
	v_min_f32_e32 v7, v7, v14
	v_max_f32_e32 v13, v5, v18
	v_min_f32_e32 v5, v5, v18
	v_max_f32_e32 v18, v4, v27
	v_min_f32_e32 v4, v4, v27
	v_max_f32_e32 v27, v109, v28
	v_min_f32_e32 v28, v109, v28
	v_max_f32_e32 v109, v26, v19
	v_min_f32_e32 v19, v26, v19
	v_max_f32_e32 v26, v2, v29
	v_min_f32_e32 v2, v2, v29
	v_max_f32_e32 v29, v11, v20
	v_min_f32_e32 v11, v11, v20
	v_max_f32_e32 v20, v12, v21
	v_min_f32_e32 v12, v12, v21
	v_max_f32_e32 v21, v3, v10
	v_min_f32_e32 v3, v3, v10
	v_max_f32_e32 v14, v17, v31
	v_min_f32_e32 v17, v17, v31
	v_max_f32_e32 v31, v22, v101
	v_min_f32_e32 v22, v22, v101
	v_max_f32_e32 v101, v9, v32
	v_min_f32_e32 v9, v9, v32
	v_max_f32_e32 v32, v8, v23
	v_min_f32_e32 v8, v8, v23
	v_max_f32_e32 v23, v16, v6
	v_min_f32_e32 v6, v16, v6
	v_max_f32_e32 v16, v7, v15
	v_min_f32_e32 v7, v7, v15
	v_max_f32_e32 v15, v24, v30
	v_min_f32_e32 v24, v24, v30
	v_max_f32_e32 v30, v25, v33
	v_min_f32_e32 v25, v25, v33
	v_max_f32_e32 v10, v13, v27
	v_min_f32_e32 v13, v13, v27
	v_max_f32_e32 v27, v18, v109
	v_min_f32_e32 v18, v18, v109
	v_max_f32_e32 v109, v5, v28
	v_min_f32_e32 v5, v5, v28
	v_max_f32_e32 v28, v4, v19
	v_min_f32_e32 v4, v4, v19
	v_max_f32_e32 v19, v12, v2
	v_min_f32_e32 v2, v12, v2
	v_max_f32_e32 v12, v3, v11
	v_min_f32_e32 v3, v3, v11
	v_max_f32_e32 v11, v20, v26
	v_min_f32_e32 v20, v20, v26
	v_max_f32_e32 v26, v21, v29
	v_min_f32_e32 v21, v21, v29
	v_max_f32_e32 v33, v14, v31
	v_min_f32_e32 v14, v14, v31
	v_max_f32_e32 v31, v17, v22
	v_min_f32_e32 v17, v17, v22
	v_max_f32_e32 v22, v101, v32
	v_min_f32_e32 v32, v101, v32
	v_max_f32_e32 v101, v9, v8
	v_min_f32_e32 v8, v9, v8
	v_max_f32_e32 v9, v7, v6
	v_min_f32_e32 v6, v7, v6
	v_max_f32_e32 v7, v16, v23
	v_min_f32_e32 v16, v16, v23
	v_max_f32_e32 v23, v25, v24
	v_min_f32_e32 v24, v25, v24
	v_max_f32_e32 v25, v30, v15
	v_min_f32_e32 v15, v30, v15
	v_max_f32_e32 v29, v10, v27
	v_min_f32_e32 v10, v10, v27
	v_max_f32_e32 v27, v13, v18
	v_min_f32_e32 v13, v13, v18
	v_max_f32_e32 v18, v109, v28
	v_min_f32_e32 v28, v109, v28
	v_max_f32_e32 v109, v5, v4
	v_min_f32_e32 v4, v5, v4
	v_max_f32_e32 v5, v3, v2
	v_min_f32_e32 v2, v3, v2
	v_max_f32_e32 v3, v12, v19
	v_min_f32_e32 v12, v12, v19
	v_max_f32_e32 v19, v21, v20
	v_min_f32_e32 v20, v21, v20
	v_max_f32_e32 v21, v26, v11
	v_min_f32_e32 v11, v26, v11
	v_max_f32_e32 v30, v33, v6
	v_min_f32_e32 v6, v33, v6
	v_max_f32_e32 v33, v14, v9
	v_min_f32_e32 v9, v14, v9
	v_max_f32_e32 v14, v31, v16
	v_min_f32_e32 v16, v31, v16
	v_max_f32_e32 v31, v17, v7
	v_min_f32_e32 v7, v17, v7
	v_max_f32_e32 v17, v22, v24
	v_min_f32_e32 v22, v22, v24
	v_max_f32_e32 v24, v32, v23
	v_min_f32_e32 v23, v32, v23
	v_max_f32_e32 v32, v101, v15
	v_min_f32_e32 v15, v101, v15
	v_max_f32_e32 v101, v8, v25
	v_min_f32_e32 v8, v8, v25
	v_max_f32_e32 v26, v29, v2
	v_min_f32_e32 v2, v29, v2
	v_max_f32_e32 v29, v10, v5
	v_min_f32_e32 v5, v10, v5
	v_max_f32_e32 v10, v27, v12
	v_min_f32_e32 v12, v27, v12
	v_max_f32_e32 v27, v13, v3
	v_min_f32_e32 v3, v13, v3
	v_max_f32_e32 v13, v18, v20
	v_min_f32_e32 v18, v18, v20
	v_max_f32_e32 v20, v28, v19
; DEV void ce(float& a, float& b) { float hi = fmaxf(a, b), lo = fminf(a, b); a = hi; b = lo; }
; DEV void sort16_desc(float (&a)[16]) {
; #pragma unroll
;   for (int k = 2; k <= 16; k <<= 1)
; #pragma unroll
;     for (int j = k >> 1; j > 0; j >>= 1)
; #pragma unroll
;       for (int i = 0; i < 16; i++) {
;         const int p = i ^ j;
;         if (p > i) { if ((i & k) == 0) ce(a[i], a[p]); else ce(a[p], a[i]); }
;       }
; }
; DEV void merge_xor(float (&l)[16], int mask) {
;   float t[16];
; #pragma unroll
;   for (int i = 0; i < 16; i++) t[i] = __shfl_xor(l[15 - i], mask);
; #pragma unroll
;   for (int i = 0; i < 16; i++) l[i] = fmaxf(l[i], t[i]);
;   bitonic16(l);
; }
; DEV void peer_top16(const bf16_t* __restrict__ pq, const bf16_t* sk  , float (&l)[16]) {
;     ...
;   sort16_desc(l);
;   sort16_desc(hi);
; #pragma unroll
;   for (int i = 0; i < 16; i++) l[i] = fmaxf(l[i], hi[15 - i]);
;   bitonic16(l);
;   merge_xor(l, 16);
;   merge_xor(l, 32);
	v_min_f32_e32 v19, v28, v19
	v_max_f32_e32 v28, v109, v11
	v_min_f32_e32 v11, v109, v11
	v_max_f32_e32 v109, v4, v21
	v_min_f32_e32 v4, v4, v21
	v_max_f32_e32 v25, v30, v17
	v_min_f32_e32 v17, v30, v17
	v_max_f32_e32 v30, v33, v24
	v_min_f32_e32 v24, v33, v24
	v_max_f32_e32 v33, v14, v32
	v_min_f32_e32 v14, v14, v32
	v_max_f32_e32 v32, v31, v101
	v_min_f32_e32 v31, v31, v101
	v_max_f32_e32 v101, v6, v22
	v_min_f32_e32 v6, v6, v22
	v_max_f32_e32 v22, v9, v23
	v_min_f32_e32 v9, v9, v23
	v_max_f32_e32 v23, v16, v15
	v_min_f32_e32 v15, v16, v15
	v_max_f32_e32 v16, v7, v8
	v_min_f32_e32 v7, v7, v8
	v_max_f32_e32 v21, v26, v13
	v_min_f32_e32 v13, v26, v13
	v_max_f32_e32 v26, v29, v20
	v_min_f32_e32 v20, v29, v20
	v_max_f32_e32 v29, v10, v28
	v_min_f32_e32 v10, v10, v28
	v_max_f32_e32 v28, v27, v109
	v_min_f32_e32 v27, v27, v109
	v_max_f32_e32 v109, v2, v18
	v_min_f32_e32 v2, v2, v18
	v_max_f32_e32 v18, v5, v19
	v_min_f32_e32 v5, v5, v19
	v_max_f32_e32 v19, v12, v11
	v_min_f32_e32 v11, v12, v11
	v_max_f32_e32 v12, v3, v4
	v_min_f32_e32 v3, v3, v4
	v_max_f32_e32 v111, v0, v43
	v_min_f32_e32 v112, v104, v39
	v_max_f32_e32 v103, v104, v39
	v_min_f32_e32 v0, v0, v43
	v_max_f32_e32 v8, v25, v33
	v_min_f32_e32 v25, v25, v33
	v_max_f32_e32 v33, v30, v32
	v_min_f32_e32 v30, v30, v32
	v_max_f32_e32 v32, v17, v14
	v_min_f32_e32 v14, v17, v14
	v_max_f32_e32 v17, v24, v31
	v_min_f32_e32 v24, v24, v31
	v_max_f32_e32 v31, v101, v23
	v_min_f32_e32 v23, v101, v23
	v_max_f32_e32 v101, v22, v16
	v_min_f32_e32 v16, v22, v16
	v_max_f32_e32 v22, v6, v15
	v_min_f32_e32 v6, v6, v15
	v_max_f32_e32 v15, v9, v7
	v_min_f32_e32 v7, v9, v7
	v_max_f32_e32 v4, v21, v29
	v_min_f32_e32 v21, v21, v29
	v_max_f32_e32 v29, v26, v28
	v_min_f32_e32 v26, v26, v28
	v_max_f32_e32 v28, v13, v10
	v_min_f32_e32 v10, v13, v10
	v_max_f32_e32 v13, v20, v27
	v_min_f32_e32 v20, v20, v27
	v_max_f32_e32 v27, v109, v19
	v_min_f32_e32 v19, v109, v19
	v_max_f32_e32 v109, v18, v12
	v_min_f32_e32 v12, v18, v12
	v_max_f32_e32 v18, v2, v11
	v_min_f32_e32 v2, v2, v11
	v_max_f32_e32 v11, v5, v3
	v_min_f32_e32 v3, v5, v3
	v_min_f32_e32 v63, v107, v108
	v_min_f32_e32 v39, v111, v103
	v_max_f32_e32 v71, v107, v108
	v_max_f32_e32 v51, v111, v103
	v_max_f32_e32 v43, v0, v112
	v_min_f32_e32 v0, v0, v112
	v_min_f32_e32 v9, v8, v33
	v_min_f32_e32 v102, v25, v30
	v_min_f32_e32 v103, v32, v17
	v_min_f32_e32 v104, v14, v24
	v_min_f32_e32 v105, v31, v101
	v_min_f32_e32 v106, v23, v16
	v_min_f32_e32 v107, v22, v15
	v_min_f32_e32 v108, v6, v7
	v_min_f32_e32 v5, v4, v29
	v_min_f32_e32 v110, v21, v26
	v_min_f32_e32 v111, v28, v13
	v_min_f32_e32 v112, v10, v20
	v_min_f32_e32 v113, v27, v109
	v_min_f32_e32 v114, v19, v12
	v_min_f32_e32 v115, v18, v11
	v_min_f32_e32 v116, v2, v3
	v_max3_f32 v8, v8, v33, v116
	v_max3_f32 v2, v9, v2, v3
	v_max3_f32 v3, v25, v30, v115
	v_max3_f32 v9, v102, v18, v11
	v_max3_f32 v11, v32, v17, v114
	v_max3_f32 v12, v103, v19, v12
	v_max3_f32 v14, v14, v24, v113
	v_max3_f32 v17, v104, v27, v109
	v_max3_f32 v18, v31, v101, v112
	v_max3_f32 v10, v105, v10, v20
	v_max3_f32 v16, v23, v16, v111
	v_max3_f32 v13, v106, v28, v13
	v_max3_f32 v15, v22, v15, v110
	v_max3_f32 v19, v107, v21, v26
	v_max3_f32 v5, v6, v7, v5
	v_max3_f32 v4, v108, v4, v29
	v_max_f32_e32 v6, v8, v18
	v_min_f32_e32 v7, v8, v18
	v_max_f32_e32 v8, v2, v10
	v_min_f32_e32 v2, v2, v10
	v_max_f32_e32 v10, v3, v16
	v_min_f32_e32 v3, v3, v16
	v_max_f32_e32 v16, v9, v13
	v_min_f32_e32 v9, v9, v13
	v_max_f32_e32 v13, v11, v15
	v_min_f32_e32 v11, v11, v15
	v_max_f32_e32 v15, v12, v19
	v_min_f32_e32 v12, v12, v19
	v_max_f32_e32 v18, v14, v5
	v_min_f32_e32 v5, v14, v5
	v_max_f32_e32 v14, v17, v4
	v_min_f32_e32 v4, v17, v4
	v_max_f32_e32 v17, v6, v13
	v_min_f32_e32 v6, v6, v13
	v_max_f32_e32 v13, v8, v15
	v_min_f32_e32 v8, v8, v15
	v_max_f32_e32 v15, v10, v18
	v_min_f32_e32 v10, v10, v18
	v_max_f32_e32 v18, v16, v14
	v_min_f32_e32 v14, v16, v14
	v_max_f32_e32 v16, v7, v11
	v_min_f32_e32 v7, v7, v11
	v_max_f32_e32 v11, v2, v12
	v_min_f32_e32 v2, v2, v12
	v_max_f32_e32 v12, v3, v5
	v_min_f32_e32 v3, v3, v5
	v_max_f32_e32 v5, v9, v4
	v_min_f32_e32 v4, v9, v4
	v_max_f32_e32 v9, v17, v15
	v_min_f32_e32 v15, v17, v15
	v_max_f32_e32 v17, v13, v18
	v_min_f32_e32 v13, v13, v18
	v_max_f32_e32 v18, v6, v10
	v_min_f32_e32 v6, v6, v10
	v_max_f32_e32 v10, v8, v14
	v_min_f32_e32 v8, v8, v14
	v_max_f32_e32 v14, v16, v12
	v_min_f32_e32 v12, v16, v12
	v_max_f32_e32 v16, v11, v5
	v_min_f32_e32 v5, v11, v5
	v_max_f32_e32 v11, v7, v3
	v_min_f32_e32 v3, v7, v3
	v_max_f32_e32 v7, v2, v4
	v_min_f32_e32 v2, v2, v4
	v_max_f32_e32 v4, v9, v17
	v_min_f32_e32 v9, v9, v17
	v_max_f32_e32 v17, v15, v13
	v_min_f32_e32 v13, v15, v13
	v_max_f32_e32 v15, v18, v10
	v_min_f32_e32 v10, v18, v10
	v_max_f32_e32 v18, v6, v8
	v_min_f32_e32 v6, v6, v8
	v_max_f32_e32 v8, v14, v16
	v_min_f32_e32 v14, v14, v16
	v_max_f32_e32 v16, v12, v5
	v_min_f32_e32 v5, v12, v5
	v_max_f32_e32 v12, v11, v7
	v_min_f32_e32 v7, v11, v7
	v_max_f32_e32 v11, v3, v2
	v_min_f32_e32 v2, v3, v2
	ds_bpermute_b32 v3, v95, v2
	ds_bpermute_b32 v19, v95, v11
	ds_bpermute_b32 v20, v95, v7
	ds_bpermute_b32 v21, v95, v12
	ds_bpermute_b32 v22, v95, v5
	ds_bpermute_b32 v23, v95, v16
	s_waitcnt lgkmcnt(5)
	ds_bpermute_b32 v24, v95, v14
	ds_bpermute_b32 v33, v95, v4
	v_max_f32_e32 v3, v4, v3
	s_waitcnt lgkmcnt(6)
	ds_bpermute_b32 v25, v95, v8
	ds_bpermute_b32 v32, v95, v9
	v_max_f32_e32 v4, v9, v19
	s_waitcnt lgkmcnt(7)
	ds_bpermute_b32 v26, v95, v6
	ds_bpermute_b32 v31, v95, v17
	v_max_f32_e32 v9, v17, v20
	s_waitcnt lgkmcnt(8)
	ds_bpermute_b32 v27, v95, v18
	ds_bpermute_b32 v30, v95, v13
	v_max_f32_e32 v13, v13, v21
	s_waitcnt lgkmcnt(9)
; DEV void merge_xor(float (&l)[16], int mask) {
;   float t[16];
; #pragma unroll
;   for (int i = 0; i < 16; i++) t[i] = __shfl_xor(l[15 - i], mask);
; #pragma unroll
;   for (int i = 0; i < 16; i++) l[i] = fmaxf(l[i], t[i]);
;   bitonic16(l);
; }
; DEV void phase_peer_score(const Params& p, int layer, int M, char* smem) {
;     ...
;     unsigned char* tab = (unsigned char*)smem + 73728 + (w * 16 + l15) * 32;
; #pragma unroll
;     for (int i = 0; i < 16; i++) { tab[i] = (unsigned char)(__float_as_uint(L0[i]) & 127u); tab[16 + i] = (unsigned char)(__float_as_uint(L1[i]) & 127u); }
	ds_bpermute_b32 v28, v95, v10
	ds_bpermute_b32 v29, v95, v15
	v_max_f32_e32 v15, v15, v22
	s_waitcnt lgkmcnt(10)
	v_max_f32_e32 v10, v10, v23
	s_waitcnt lgkmcnt(9)
	v_max_f32_e32 v17, v18, v24
	s_waitcnt lgkmcnt(7)
	v_max_f32_e32 v6, v6, v25
	s_waitcnt lgkmcnt(5)
	v_max_f32_e32 v8, v8, v26
	s_waitcnt lgkmcnt(3)
	v_max_f32_e32 v14, v14, v27
	s_waitcnt lgkmcnt(1)
	v_max_f32_e32 v16, v16, v28
	s_waitcnt lgkmcnt(0)
	v_max_f32_e32 v5, v5, v29
	v_max_f32_e32 v12, v12, v30
	v_max_f32_e32 v7, v7, v31
	v_max_f32_e32 v11, v11, v32
	v_max_f32_e32 v2, v2, v33
	v_max_f32_e32 v18, v3, v8
	v_min_f32_e32 v3, v3, v8
	v_max_f32_e32 v8, v4, v14
	v_min_f32_e32 v4, v4, v14
	v_max_f32_e32 v14, v9, v16
	v_min_f32_e32 v9, v9, v16
	v_max_f32_e32 v16, v13, v5
	v_min_f32_e32 v5, v13, v5
	v_max_f32_e32 v13, v15, v12
	v_min_f32_e32 v12, v15, v12
	v_max_f32_e32 v15, v10, v7
	v_min_f32_e32 v7, v10, v7
	v_max_f32_e32 v10, v17, v11
	v_min_f32_e32 v11, v17, v11
	v_max_f32_e32 v17, v6, v2
	v_min_f32_e32 v2, v6, v2
	v_max_f32_e32 v6, v18, v13
	v_min_f32_e32 v13, v18, v13
	v_max_f32_e32 v18, v8, v15
	v_min_f32_e32 v8, v8, v15
	v_max_f32_e32 v15, v14, v10
	v_min_f32_e32 v10, v14, v10
	v_max_f32_e32 v14, v16, v17
	v_min_f32_e32 v16, v16, v17
	v_max_f32_e32 v17, v3, v12
	v_min_f32_e32 v3, v3, v12
	v_max_f32_e32 v12, v4, v7
	v_min_f32_e32 v4, v4, v7
	v_max_f32_e32 v7, v9, v11
	v_min_f32_e32 v9, v9, v11
	v_max_f32_e32 v11, v5, v2
	v_min_f32_e32 v2, v5, v2
	v_max_f32_e32 v5, v6, v15
	v_min_f32_e32 v6, v6, v15
	v_max_f32_e32 v15, v18, v14
	v_min_f32_e32 v14, v18, v14
	v_max_f32_e32 v18, v13, v10
	v_min_f32_e32 v10, v13, v10
	v_max_f32_e32 v13, v8, v16
	v_min_f32_e32 v8, v8, v16
	v_max_f32_e32 v16, v17, v7
	v_min_f32_e32 v7, v17, v7
	v_max_f32_e32 v17, v12, v11
	v_min_f32_e32 v11, v12, v11
	v_max_f32_e32 v12, v3, v9
	v_min_f32_e32 v3, v3, v9
	v_max_f32_e32 v9, v4, v2
	v_min_f32_e32 v2, v4, v2
	v_max_f32_e32 v4, v5, v15
	v_min_f32_e32 v5, v5, v15
	v_max_f32_e32 v15, v6, v14
	v_min_f32_e32 v6, v6, v14
	v_max_f32_e32 v14, v18, v13
	v_min_f32_e32 v13, v18, v13
	v_max_f32_e32 v18, v10, v8
	v_min_f32_e32 v8, v10, v8
	v_max_f32_e32 v10, v16, v17
	v_min_f32_e32 v16, v16, v17
	v_max_f32_e32 v17, v7, v11
	v_min_f32_e32 v7, v7, v11
	v_max_f32_e32 v11, v12, v9
	v_min_f32_e32 v9, v12, v9
	v_max_f32_e32 v12, v3, v2
	v_min_f32_e32 v2, v3, v2
	ds_bpermute_b32 v3, v99, v2
	ds_bpermute_b32 v19, v99, v12
	ds_bpermute_b32 v20, v99, v9
	ds_bpermute_b32 v21, v99, v11
	ds_bpermute_b32 v22, v99, v7
	ds_bpermute_b32 v23, v99, v17
	s_waitcnt lgkmcnt(5)
	ds_bpermute_b32 v24, v99, v16
	ds_bpermute_b32 v33, v99, v4
	v_max_f32_e32 v3, v4, v3
	s_waitcnt lgkmcnt(6)
	ds_bpermute_b32 v25, v99, v10
	ds_bpermute_b32 v32, v99, v5
	v_max_f32_e32 v4, v5, v19
	s_waitcnt lgkmcnt(7)
	ds_bpermute_b32 v26, v99, v8
	ds_bpermute_b32 v31, v99, v15
	v_max_f32_e32 v5, v15, v20
	s_waitcnt lgkmcnt(8)
	ds_bpermute_b32 v27, v99, v18
	ds_bpermute_b32 v30, v99, v6
	v_max_f32_e32 v6, v6, v21
	s_waitcnt lgkmcnt(9)
	ds_bpermute_b32 v28, v99, v13
	ds_bpermute_b32 v29, v99, v14
	v_max_f32_e32 v14, v14, v22
	s_waitcnt lgkmcnt(10)
	v_max_f32_e32 v13, v13, v23
	s_waitcnt lgkmcnt(9)
	v_max_f32_e32 v15, v18, v24
	s_waitcnt lgkmcnt(7)
	v_max_f32_e32 v8, v8, v25
	s_waitcnt lgkmcnt(5)
	v_max_f32_e32 v10, v10, v26
	s_waitcnt lgkmcnt(3)
	v_max_f32_e32 v16, v16, v27
	s_waitcnt lgkmcnt(1)
	v_max_f32_e32 v17, v17, v28
	s_waitcnt lgkmcnt(0)
	v_max_f32_e32 v7, v7, v29
	v_max_f32_e32 v11, v11, v30
	v_max_f32_e32 v9, v9, v31
	v_max_f32_e32 v12, v12, v32
	v_max_f32_e32 v2, v2, v33
	v_max_f32_e32 v18, v3, v10
	v_min_f32_e32 v3, v3, v10
	v_max_f32_e32 v10, v4, v16
	v_min_f32_e32 v4, v4, v16
	v_max_f32_e32 v16, v5, v17
	v_min_f32_e32 v5, v5, v17
	v_max_f32_e32 v17, v6, v7
	v_min_f32_e32 v6, v6, v7
	v_max_f32_e32 v7, v14, v11
	v_min_f32_e32 v11, v14, v11
	v_max_f32_e32 v14, v13, v9
	v_min_f32_e32 v9, v13, v9
	v_max_f32_e32 v13, v15, v12
	v_min_f32_e32 v12, v15, v12
	v_max_f32_e32 v15, v8, v2
	v_min_f32_e32 v2, v8, v2
	v_max_f32_e32 v8, v18, v7
	v_min_f32_e32 v7, v18, v7
	v_max_f32_e32 v18, v10, v14
	v_min_f32_e32 v10, v10, v14
	v_max_f32_e32 v14, v16, v13
	v_min_f32_e32 v13, v16, v13
	v_max_f32_e32 v16, v17, v15
	v_min_f32_e32 v15, v17, v15
	v_max_f32_e32 v17, v3, v11
	v_min_f32_e32 v3, v3, v11
	v_max_f32_e32 v11, v4, v9
	v_min_f32_e32 v4, v4, v9
	v_max_f32_e32 v9, v5, v12
	v_min_f32_e32 v5, v5, v12
	v_max_f32_e32 v12, v6, v2
	v_min_f32_e32 v2, v6, v2
	v_max_f32_e32 v6, v8, v14
	v_min_f32_e32 v8, v8, v14
	v_max_f32_e32 v14, v18, v16
	v_min_f32_e32 v16, v18, v16
	v_max_f32_e32 v18, v7, v13
	v_max_f32_e32 v19, v10, v15
	s_movk_i32 s0, 0x7f
	v_min_f32_e32 v13, v7, v13
	v_min_f32_e32 v10, v10, v15
	v_max_f32_e32 v15, v17, v9
	v_min_f32_e32 v21, v17, v9
	v_max_f32_e32 v17, v11, v12
	v_min_f32_e32 v22, v11, v12
	v_max_f32_e32 v23, v3, v5
	v_min_f32_e32 v3, v3, v5
	v_max_f32_e32 v5, v4, v2
	v_min_f32_e32 v24, v4, v2
	v_max_f32_e32 v9, v18, v19
	v_min_f32_e32 v12, v18, v19
	v_and_b32_sdwa v18, v63, s0 dst_sel:BYTE_1 dst_unused:UNUSED_PAD src0_sel:DWORD src1_sel:DWORD
	v_max_f32_e32 v2, v6, v14
	v_min_f32_e32 v4, v6, v14
	v_max_f32_e32 v11, v13, v10
	v_min_f32_e32 v10, v13, v10
	v_max_f32_e32 v14, v23, v5
	v_min_f32_e32 v13, v23, v5
	v_max_f32_e32 v6, v3, v24
	v_min_f32_e32 v5, v3, v24
	v_and_b32_sdwa v3, v75, s0 dst_sel:BYTE_1 dst_unused:UNUSED_PAD src0_sel:DWORD src1_sel:DWORD
	v_bitop3_b16 v18, v71, v18, s0 bitop3:0xec
	v_bitop3_b16 v3, v79, v3, s0 bitop3:0xec
	v_lshlrev_b32_e32 v18, 16, v18
	v_or_b32_sdwa v23, v3, v18 dst_sel:DWORD dst_unused:UNUSED_PAD src0_sel:WORD_0 src1_sel:DWORD
	v_and_b32_sdwa v18, v83, s0 dst_sel:BYTE_1 dst_unused:UNUSED_PAD src0_sel:DWORD src1_sel:DWORD
; DEV void ce(float& a, float& b) { float hi = fmaxf(a, b), lo = fminf(a, b); a = hi; b = lo; }
; DEV void phase_peer_score(const Params& p, int layer, int M, char* smem) {
;     ...
; #pragma unroll
;     for (int i = 0; i < 16; i++) R[i] = -3.0e38f;
; #pragma unroll
;     for (int i = 0; i < 16; i++)
; #pragma unroll
;       for (int j = 0; j < 16; j++)
;         if ((i + 1) * (j + 1) <= 16) {
;           float v = L0[i] + L1[j];
;           v = __uint_as_float((__float_as_uint(v) & ~255u) | (unsigned)(i * 16 + j));
; #pragma unroll
;           for (int t = 0; t < 16; t++)
;             if (t >= (i + 1) * (j + 1) - 1) ce(R[t], v);
;         }
;     unsigned char* tab = (unsigned char*)smem + 73728 + (w * 16 + l15) * 32;
; #pragma unroll
;     for (int i = 0; i < 16; i++) { tab[i] = (unsigned char)(__float_as_uint(L0[i]) & 127u); tab[16 + i] = (unsigned char)(__float_as_uint(L1[i]) & 127u); }
	v_and_b32_sdwa v3, v91, s0 dst_sel:BYTE_1 dst_unused:UNUSED_PAD src0_sel:DWORD src1_sel:DWORD
	v_bitop3_b16 v18, v87, v18, s0 bitop3:0xec
	v_bitop3_b16 v3, v100, v3, s0 bitop3:0xec
	v_lshlrev_b32_e32 v18, 16, v18
	v_max_f32_e32 v7, v8, v16
	v_min_f32_e32 v8, v8, v16
	v_max_f32_e32 v20, v15, v17
	v_min_f32_e32 v17, v15, v17
	v_max_f32_e32 v16, v21, v22
	v_min_f32_e32 v15, v21, v22
	v_or_b32_sdwa v22, v3, v18 dst_sel:DWORD dst_unused:UNUSED_PAD src0_sel:WORD_0 src1_sel:DWORD
	v_and_b32_sdwa v18, v10, s0 dst_sel:BYTE_1 dst_unused:UNUSED_PAD src0_sel:DWORD src1_sel:DWORD
	v_and_b32_sdwa v3, v12, s0 dst_sel:BYTE_1 dst_unused:UNUSED_PAD src0_sel:DWORD src1_sel:DWORD
	v_bitop3_b16 v18, v11, v18, s0 bitop3:0xec
	v_bitop3_b16 v3, v9, v3, s0 bitop3:0xec
	v_lshlrev_b32_e32 v18, 16, v18
	v_or_b32_sdwa v27, v3, v18 dst_sel:DWORD dst_unused:UNUSED_PAD src0_sel:WORD_0 src1_sel:DWORD
	v_and_b32_sdwa v18, v8, s0 dst_sel:BYTE_1 dst_unused:UNUSED_PAD src0_sel:DWORD src1_sel:DWORD
	v_and_b32_sdwa v3, v4, s0 dst_sel:BYTE_1 dst_unused:UNUSED_PAD src0_sel:DWORD src1_sel:DWORD
	v_bitop3_b16 v18, v7, v18, s0 bitop3:0xec
	v_bitop3_b16 v3, v2, v3, s0 bitop3:0xec
	v_lshlrev_b32_e32 v18, 16, v18
	v_or_b32_sdwa v26, v3, v18 dst_sel:DWORD dst_unused:UNUSED_PAD src0_sel:WORD_0 src1_sel:DWORD
	v_and_b32_sdwa v18, v0, s0 dst_sel:BYTE_1 dst_unused:UNUSED_PAD src0_sel:DWORD src1_sel:DWORD
	v_and_b32_sdwa v3, v39, s0 dst_sel:BYTE_1 dst_unused:UNUSED_PAD src0_sel:DWORD src1_sel:DWORD
	v_bitop3_b16 v18, v43, v18, s0 bitop3:0xec
	v_bitop3_b16 v3, v51, v3, s0 bitop3:0xec
	v_lshlrev_b32_e32 v18, 16, v18
	v_or_b32_sdwa v25, v3, v18 dst_sel:DWORD dst_unused:UNUSED_PAD src0_sel:WORD_0 src1_sel:DWORD
	v_and_b32_sdwa v18, v47, s0 dst_sel:BYTE_1 dst_unused:UNUSED_PAD src0_sel:DWORD src1_sel:DWORD
	v_and_b32_sdwa v3, v59, s0 dst_sel:BYTE_1 dst_unused:UNUSED_PAD src0_sel:DWORD src1_sel:DWORD
	v_bitop3_b16 v18, v55, v18, s0 bitop3:0xec
	v_bitop3_b16 v3, v67, v3, s0 bitop3:0xec
	v_lshlrev_b32_e32 v18, 16, v18
	v_or_b32_sdwa v24, v3, v18 dst_sel:DWORD dst_unused:UNUSED_PAD src0_sel:WORD_0 src1_sel:DWORD
	v_and_b32_sdwa v18, v5, s0 dst_sel:BYTE_1 dst_unused:UNUSED_PAD src0_sel:DWORD src1_sel:DWORD
	v_and_b32_sdwa v3, v13, s0 dst_sel:BYTE_1 dst_unused:UNUSED_PAD src0_sel:DWORD src1_sel:DWORD
	v_bitop3_b16 v18, v6, v18, s0 bitop3:0xec
	v_bitop3_b16 v3, v14, v3, s0 bitop3:0xec
	v_lshlrev_b32_e32 v18, 16, v18
	v_or_b32_sdwa v29, v3, v18 dst_sel:DWORD dst_unused:UNUSED_PAD src0_sel:WORD_0 src1_sel:DWORD
	v_and_b32_sdwa v18, v15, s0 dst_sel:BYTE_1 dst_unused:UNUSED_PAD src0_sel:DWORD src1_sel:DWORD
	v_and_b32_sdwa v3, v17, s0 dst_sel:BYTE_1 dst_unused:UNUSED_PAD src0_sel:DWORD src1_sel:DWORD
	v_bitop3_b16 v18, v16, v18, s0 bitop3:0xec
	v_bitop3_b16 v3, v20, v3, s0 bitop3:0xec
	v_lshlrev_b32_e32 v18, 16, v18
	v_or_b32_sdwa v28, v3, v18 dst_sel:DWORD dst_unused:UNUSED_PAD src0_sel:WORD_0 src1_sel:DWORD
	ds_write_b128 v138, v[22:25]
	ds_write_b128 v138, v[26:29] offset:16
	s_and_saveexec_b64 s[14:15], s[38:39]
	s_cbranch_execz .LBB0_162
	s_movk_i32 s0, 0xff00
	v_add_f32_e32 v164, v100, v2
	v_and_or_b32 v164, v164, s0, 0
	v_max_f32_e32 v148, 0xff61b1e6, v164
	v_add_f32_e32 v164, v100, v4
	v_and_or_b32 v164, v164, s0, 1
	v_max_f32_e32 v149, 0xff61b1e6, v164
	v_add_f32_e32 v164, v100, v7
	v_and_or_b32 v164, v164, s0, 2
	v_max_f32_e32 v150, 0xff61b1e6, v164
	v_add_f32_e32 v164, v100, v8
	v_and_or_b32 v164, v164, s0, 3
	v_max_f32_e32 v151, 0xff61b1e6, v164
	v_add_f32_e32 v164, v100, v9
	v_and_or_b32 v164, v164, s0, 4
	v_max_f32_e32 v152, 0xff61b1e6, v164
	v_add_f32_e32 v164, v100, v12
	v_and_or_b32 v164, v164, s0, 5
	v_max_f32_e32 v153, 0xff61b1e6, v164
	v_add_f32_e32 v164, v100, v11
	v_and_or_b32 v164, v164, s0, 6
	v_max_f32_e32 v154, 0xff61b1e6, v164
	v_add_f32_e32 v164, v100, v10
	v_and_or_b32 v164, v164, s0, 7
	v_max_f32_e32 v155, 0xff61b1e6, v164
	v_add_f32_e32 v164, v100, v20
	v_and_or_b32 v164, v164, s0, 8
	v_max_f32_e32 v156, 0xff61b1e6, v164
	v_add_f32_e32 v164, v100, v17
	v_and_or_b32 v164, v164, s0, 9
	v_max_f32_e32 v157, 0xff61b1e6, v164
	v_add_f32_e32 v164, v100, v16
	v_and_or_b32 v164, v164, s0, 10
	v_max_f32_e32 v158, 0xff61b1e6, v164
	v_add_f32_e32 v164, v100, v15
	v_and_or_b32 v164, v164, s0, 11
	v_max_f32_e32 v159, 0xff61b1e6, v164
	v_add_f32_e32 v164, v100, v14
	v_and_or_b32 v164, v164, s0, 12
	v_max_f32_e32 v160, 0xff61b1e6, v164
	v_add_f32_e32 v164, v100, v13
	v_and_or_b32 v164, v164, s0, 13
	v_max_f32_e32 v161, 0xff61b1e6, v164
	v_add_f32_e32 v164, v100, v6
	v_and_or_b32 v164, v164, s0, 14
	v_max_f32_e32 v162, 0xff61b1e6, v164
	v_add_f32_e32 v164, v100, v5
	v_and_or_b32 v164, v164, s0, 15
	v_max_f32_e32 v163, 0xff61b1e6, v164
	v_add_f32_e32 v164, v91, v2
	v_and_or_b32 v164, v164, s0, 16
	v_med3_f32 v163, v162, v163, v164
	v_med3_f32 v162, v161, v162, v164
	v_med3_f32 v161, v160, v161, v164
	v_med3_f32 v160, v159, v160, v164
	v_med3_f32 v159, v158, v159, v164
	v_med3_f32 v158, v157, v158, v164
	v_med3_f32 v157, v156, v157, v164
	v_med3_f32 v156, v155, v156, v164
	v_med3_f32 v155, v154, v155, v164
	v_med3_f32 v154, v153, v154, v164
	v_med3_f32 v153, v152, v153, v164
	v_med3_f32 v152, v151, v152, v164
	v_med3_f32 v151, v150, v151, v164
	v_med3_f32 v150, v149, v150, v164
	v_max_f32_e32 v149, v149, v164
	v_add_f32_e32 v164, v91, v4
	v_and_or_b32 v164, v164, s0, 17
	v_med3_f32 v163, v162, v163, v164
	v_med3_f32 v162, v161, v162, v164
	v_med3_f32 v161, v160, v161, v164
	v_med3_f32 v160, v159, v160, v164
	v_med3_f32 v159, v158, v159, v164
	v_med3_f32 v158, v157, v158, v164
	v_med3_f32 v157, v156, v157, v164
	v_med3_f32 v156, v155, v156, v164
	v_med3_f32 v155, v154, v155, v164
; DEV void ce(float& a, float& b) { float hi = fmaxf(a, b), lo = fminf(a, b); a = hi; b = lo; }
; DEV void phase_peer_score(const Params& p, int layer, int M, char* smem) {
;     ...
; #pragma unroll
;     for (int i = 0; i < 16; i++)
; #pragma unroll
;       for (int j = 0; j < 16; j++)
;         if ((i + 1) * (j + 1) <= 16) {
;           float v = L0[i] + L1[j];
;           v = __uint_as_float((__float_as_uint(v) & ~255u) | (unsigned)(i * 16 + j));
; #pragma unroll
;           for (int t = 0; t < 16; t++)
;             if (t >= (i + 1) * (j + 1) - 1) ce(R[t], v);
;         }
	v_med3_f32 v154, v153, v154, v164
	v_med3_f32 v153, v152, v153, v164
	v_med3_f32 v152, v151, v152, v164
	v_max_f32_e32 v151, v151, v164
	v_add_f32_e32 v164, v91, v7
	v_and_or_b32 v164, v164, s0, 18
	v_med3_f32 v163, v162, v163, v164
	v_med3_f32 v162, v161, v162, v164
	v_med3_f32 v161, v160, v161, v164
	v_med3_f32 v160, v159, v160, v164
	v_med3_f32 v159, v158, v159, v164
	v_med3_f32 v158, v157, v158, v164
	v_med3_f32 v157, v156, v157, v164
	v_med3_f32 v156, v155, v156, v164
	v_med3_f32 v155, v154, v155, v164
	v_med3_f32 v154, v153, v154, v164
	v_max_f32_e32 v153, v153, v164
	v_add_f32_e32 v164, v91, v8
	v_and_or_b32 v164, v164, s0, 19
	v_med3_f32 v163, v162, v163, v164
	v_med3_f32 v162, v161, v162, v164
	v_med3_f32 v161, v160, v161, v164
	v_med3_f32 v160, v159, v160, v164
	v_med3_f32 v159, v158, v159, v164
	v_med3_f32 v158, v157, v158, v164
	v_med3_f32 v157, v156, v157, v164
	v_med3_f32 v156, v155, v156, v164
	v_max_f32_e32 v155, v155, v164
	v_add_f32_e32 v164, v91, v9
	v_and_or_b32 v164, v164, s0, 20
	v_med3_f32 v163, v162, v163, v164
	v_med3_f32 v162, v161, v162, v164
	v_med3_f32 v161, v160, v161, v164
	v_med3_f32 v160, v159, v160, v164
	v_med3_f32 v159, v158, v159, v164
	v_med3_f32 v158, v157, v158, v164
	v_max_f32_e32 v157, v157, v164
	v_add_f32_e32 v164, v91, v12
	v_and_or_b32 v164, v164, s0, 21
	v_med3_f32 v163, v162, v163, v164
	v_med3_f32 v162, v161, v162, v164
	v_med3_f32 v161, v160, v161, v164
	v_med3_f32 v160, v159, v160, v164
	v_max_f32_e32 v159, v159, v164
	v_add_f32_e32 v164, v91, v11
	v_and_or_b32 v164, v164, s0, 22
	v_med3_f32 v163, v162, v163, v164
	v_med3_f32 v162, v161, v162, v164
	v_max_f32_e32 v161, v161, v164
	v_add_f32_e32 v164, v91, v10
	v_and_or_b32 v164, v164, s0, 23
	v_max_f32_e32 v163, v163, v164
	v_add_f32_e32 v164, v87, v2
	v_and_or_b32 v164, v164, s0, 32
	v_med3_f32 v163, v162, v163, v164
	v_med3_f32 v162, v161, v162, v164
	v_med3_f32 v161, v160, v161, v164
	v_med3_f32 v160, v159, v160, v164
	v_med3_f32 v159, v158, v159, v164
	v_med3_f32 v158, v157, v158, v164
	v_med3_f32 v157, v156, v157, v164
	v_med3_f32 v156, v155, v156, v164
	v_med3_f32 v155, v154, v155, v164
	v_med3_f32 v154, v153, v154, v164
	v_med3_f32 v153, v152, v153, v164
	v_med3_f32 v152, v151, v152, v164
	v_med3_f32 v151, v150, v151, v164
	v_max_f32_e32 v150, v150, v164
	v_add_f32_e32 v164, v87, v4
	v_and_or_b32 v164, v164, s0, 33
	v_med3_f32 v163, v162, v163, v164
	v_med3_f32 v162, v161, v162, v164
	v_med3_f32 v161, v160, v161, v164
	v_med3_f32 v160, v159, v160, v164
	v_med3_f32 v159, v158, v159, v164
	v_med3_f32 v158, v157, v158, v164
	v_med3_f32 v157, v156, v157, v164
	v_med3_f32 v156, v155, v156, v164
	v_med3_f32 v155, v154, v155, v164
	v_med3_f32 v154, v153, v154, v164
	v_max_f32_e32 v153, v153, v164
	v_add_f32_e32 v164, v87, v7
	v_and_or_b32 v164, v164, s0, 34
	v_med3_f32 v163, v162, v163, v164
	v_med3_f32 v162, v161, v162, v164
	v_med3_f32 v161, v160, v161, v164
	v_med3_f32 v160, v159, v160, v164
	v_med3_f32 v159, v158, v159, v164
	v_med3_f32 v158, v157, v158, v164
	v_med3_f32 v157, v156, v157, v164
	v_max_f32_e32 v156, v156, v164
	v_add_f32_e32 v164, v87, v8
	v_and_or_b32 v164, v164, s0, 35
	v_med3_f32 v163, v162, v163, v164
	v_med3_f32 v162, v161, v162, v164
	v_med3_f32 v161, v160, v161, v164
	v_med3_f32 v160, v159, v160, v164
	v_max_f32_e32 v159, v159, v164
	v_add_f32_e32 v164, v87, v9
	v_and_or_b32 v164, v164, s0, 36
	v_med3_f32 v163, v162, v163, v164
	v_max_f32_e32 v162, v162, v164
	v_add_f32_e32 v164, v83, v2
	v_and_or_b32 v164, v164, s0, 48
	v_med3_f32 v163, v162, v163, v164
	v_med3_f32 v162, v161, v162, v164
	v_med3_f32 v161, v160, v161, v164
	v_med3_f32 v160, v159, v160, v164
	v_med3_f32 v159, v158, v159, v164
	v_med3_f32 v158, v157, v158, v164
	v_med3_f32 v157, v156, v157, v164
	v_med3_f32 v156, v155, v156, v164
	v_med3_f32 v155, v154, v155, v164
	v_med3_f32 v154, v153, v154, v164
	v_med3_f32 v153, v152, v153, v164
	v_med3_f32 v152, v151, v152, v164
	v_max_f32_e32 v151, v151, v164
	v_add_f32_e32 v164, v83, v4
	v_and_or_b32 v164, v164, s0, 49
	v_med3_f32 v163, v162, v163, v164
	v_med3_f32 v162, v161, v162, v164
	v_med3_f32 v161, v160, v161, v164
	v_med3_f32 v160, v159, v160, v164
	v_med3_f32 v159, v158, v159, v164
	v_med3_f32 v158, v157, v158, v164
	v_med3_f32 v157, v156, v157, v164
	v_med3_f32 v156, v155, v156, v164
	v_max_f32_e32 v155, v155, v164
	v_add_f32_e32 v164, v83, v7
	v_and_or_b32 v164, v164, s0, 50
	v_med3_f32 v163, v162, v163, v164
	v_med3_f32 v162, v161, v162, v164
	v_med3_f32 v161, v160, v161, v164
	v_med3_f32 v160, v159, v160, v164
	v_max_f32_e32 v159, v159, v164
	v_add_f32_e32 v164, v83, v8
	v_and_or_b32 v164, v164, s0, 51
	v_max_f32_e32 v163, v163, v164
	v_add_f32_e32 v164, v79, v2
	v_and_or_b32 v164, v164, s0, 64
	v_med3_f32 v163, v162, v163, v164
	v_med3_f32 v162, v161, v162, v164
	v_med3_f32 v161, v160, v161, v164
	v_med3_f32 v160, v159, v160, v164
	v_med3_f32 v159, v158, v159, v164
	v_med3_f32 v158, v157, v158, v164
	v_med3_f32 v157, v156, v157, v164
	v_med3_f32 v156, v155, v156, v164
	v_med3_f32 v155, v154, v155, v164
	v_med3_f32 v154, v153, v154, v164
	v_med3_f32 v153, v152, v153, v164
	v_max_f32_e32 v152, v152, v164
	v_add_f32_e32 v164, v79, v4
	v_and_b32_e32 v164, 0xffffff00, v164
	v_or_b32_e32 v164, 0x41, v164
	v_med3_f32 v163, v162, v163, v164
	v_med3_f32 v162, v161, v162, v164
	v_med3_f32 v161, v160, v161, v164
	v_med3_f32 v160, v159, v160, v164
	v_med3_f32 v159, v158, v159, v164
	v_med3_f32 v158, v157, v158, v164
	v_max_f32_e32 v157, v157, v164
	v_add_f32_e32 v164, v79, v7
	v_and_b32_e32 v164, 0xffffff00, v164
	v_or_b32_e32 v164, 0x42, v164
	v_med3_f32 v163, v162, v163, v164
	v_max_f32_e32 v162, v162, v164
; DEV void ce(float& a, float& b) { float hi = fmaxf(a, b), lo = fminf(a, b); a = hi; b = lo; }
; DEV void phase_peer_score(const Params& p, int layer, int M, char* smem) {
;     ...
; #pragma unroll
;     for (int i = 0; i < 16; i++)
; #pragma unroll
;       for (int j = 0; j < 16; j++)
;         if ((i + 1) * (j + 1) <= 16) {
;           float v = L0[i] + L1[j];
;           v = __uint_as_float((__float_as_uint(v) & ~255u) | (unsigned)(i * 16 + j));
; #pragma unroll
;           for (int t = 0; t < 16; t++)
;             if (t >= (i + 1) * (j + 1) - 1) ce(R[t], v);
;         }
;     unsigned char* tab = (unsigned char*)smem + 73728 + (w * 16 + l15) * 32;
; #pragma unroll
;     for (int i = 0; i < 16; i++) { tab[i] = (unsigned char)(__float_as_uint(L0[i]) & 127u); tab[16 + i] = (unsigned char)(__float_as_uint(L1[i]) & 127u); }
;     float ev[16]; float sum = 0.f;
; #pragma unroll
;     for (int t = 0; t < 16; t++) { ev[t] = __expf(R[t] - R[0]); sum += ev[t]; }
;     const float inv = 1.f / sum;
;     int eid[16];
; #pragma unroll
;     for (int t = 0; t < 16; t++) {
;       unsigned code = __float_as_uint(R[t]) & 255u;
;       eid[t] = (int)tab[code >> 4] * 128 + (int)tab[16 + (code & 15u)];
;     }
	v_add_f32_e32 v164, v75, v2
	v_and_b32_e32 v164, 0xffffff00, v164
	v_or_b32_e32 v164, 0x50, v164
	v_med3_f32 v163, v162, v163, v164
	v_med3_f32 v162, v161, v162, v164
	v_med3_f32 v161, v160, v161, v164
	v_med3_f32 v160, v159, v160, v164
	v_med3_f32 v159, v158, v159, v164
	v_med3_f32 v158, v157, v158, v164
	v_med3_f32 v157, v156, v157, v164
	v_med3_f32 v156, v155, v156, v164
	v_med3_f32 v155, v154, v155, v164
	v_med3_f32 v154, v153, v154, v164
	v_max_f32_e32 v153, v153, v164
	v_add_f32_e32 v164, v75, v4
	v_and_b32_e32 v164, 0xffffff00, v164
	v_or_b32_e32 v164, 0x51, v164
	v_med3_f32 v163, v162, v163, v164
	v_med3_f32 v162, v161, v162, v164
	v_med3_f32 v161, v160, v161, v164
	v_med3_f32 v160, v159, v160, v164
	v_max_f32_e32 v159, v159, v164
	v_add_f32_e32 v164, v71, v2
	v_and_b32_e32 v164, 0xffffff00, v164
	v_or_b32_e32 v164, 0x60, v164
	v_med3_f32 v163, v162, v163, v164
	v_med3_f32 v162, v161, v162, v164
	v_med3_f32 v161, v160, v161, v164
	v_med3_f32 v160, v159, v160, v164
	v_med3_f32 v159, v158, v159, v164
	v_med3_f32 v158, v157, v158, v164
	v_med3_f32 v157, v156, v157, v164
	v_med3_f32 v156, v155, v156, v164
	v_med3_f32 v155, v154, v155, v164
	v_max_f32_e32 v154, v154, v164
	v_add_f32_e32 v164, v71, v4
	v_and_b32_e32 v164, 0xffffff00, v164
	v_or_b32_e32 v164, 0x61, v164
	v_med3_f32 v163, v162, v163, v164
	v_med3_f32 v162, v161, v162, v164
	v_max_f32_e32 v161, v161, v164
	v_add_f32_e32 v164, v63, v2
	v_and_b32_e32 v164, 0xffffff00, v164
	v_or_b32_e32 v164, 0x70, v164
	v_med3_f32 v163, v162, v163, v164
	v_med3_f32 v162, v161, v162, v164
	v_med3_f32 v161, v160, v161, v164
	v_med3_f32 v160, v159, v160, v164
	v_med3_f32 v159, v158, v159, v164
	v_med3_f32 v158, v157, v158, v164
	v_med3_f32 v157, v156, v157, v164
	v_med3_f32 v156, v155, v156, v164
	v_max_f32_e32 v155, v155, v164
	v_add_f32_e32 v164, v63, v4
	v_and_b32_e32 v164, 0xffffff00, v164
	v_or_b32_e32 v164, 0x71, v164
	v_max_f32_e32 v163, v163, v164
	v_add_f32_e32 v164, v67, v2
	v_and_b32_e32 v164, 0xffffff00, v164
	v_or_b32_e32 v164, 0x80, v164
	v_med3_f32 v163, v162, v163, v164
	v_med3_f32 v162, v161, v162, v164
	v_med3_f32 v161, v160, v161, v164
	v_med3_f32 v160, v159, v160, v164
	v_med3_f32 v159, v158, v159, v164
	v_med3_f32 v158, v157, v158, v164
	v_med3_f32 v157, v156, v157, v164
	v_max_f32_e32 v156, v156, v164
	v_add_f32_e32 v164, v59, v2
	v_and_b32_e32 v164, 0xffffff00, v164
	v_or_b32_e32 v164, 0x90, v164
	v_med3_f32 v163, v162, v163, v164
	v_med3_f32 v162, v161, v162, v164
	v_med3_f32 v161, v160, v161, v164
	v_med3_f32 v160, v159, v160, v164
	v_med3_f32 v159, v158, v159, v164
	v_med3_f32 v158, v157, v158, v164
	v_max_f32_e32 v157, v157, v164
	v_add_f32_e32 v164, v55, v2
	v_and_b32_e32 v164, 0xffffff00, v164
	v_or_b32_e32 v164, 0xa0, v164
	v_med3_f32 v163, v162, v163, v164
	v_med3_f32 v162, v161, v162, v164
	v_med3_f32 v161, v160, v161, v164
	v_med3_f32 v160, v159, v160, v164
	v_med3_f32 v159, v158, v159, v164
	v_max_f32_e32 v158, v158, v164
	v_add_f32_e32 v164, v47, v2
	v_and_b32_e32 v164, 0xffffff00, v164
	v_or_b32_e32 v164, 0xb0, v164
	v_med3_f32 v163, v162, v163, v164
	v_med3_f32 v162, v161, v162, v164
	v_med3_f32 v161, v160, v161, v164
	v_med3_f32 v160, v159, v160, v164
	v_max_f32_e32 v159, v159, v164
	v_add_f32_e32 v164, v51, v2
	v_and_b32_e32 v164, 0xffffff00, v164
	v_or_b32_e32 v164, 0xc0, v164
	v_med3_f32 v163, v162, v163, v164
	v_med3_f32 v162, v161, v162, v164
	v_med3_f32 v161, v160, v161, v164
	v_max_f32_e32 v160, v160, v164
	v_add_f32_e32 v164, v39, v2
	v_and_b32_e32 v164, 0xffffff00, v164
	v_or_b32_e32 v164, 0xd0, v164
	v_med3_f32 v163, v162, v163, v164
	v_med3_f32 v162, v161, v162, v164
	v_max_f32_e32 v161, v161, v164
	v_add_f32_e32 v164, v43, v2
	v_and_b32_e32 v164, 0xffffff00, v164
	v_or_b32_e32 v164, 0xe0, v164
	v_med3_f32 v163, v162, v163, v164
	v_max_f32_e32 v162, v162, v164
	v_add_f32_e32 v164, v0, v2
	v_and_b32_e32 v164, 0xffffff00, v164
	v_or_b32_e32 v164, 0xf0, v164
	v_max_f32_e32 v163, v163, v164
	s_lshl_b32 s0, s18, 3
	s_andn2_b32 s0, s0, 63
	v_add_u32_e32 v18, s0, v117
	s_movk_i32 s0, 0xff00
	v_sub_f32_e32 v5, v149, v148
	v_mul_f32_e32 v5, 0x3fb8aa3b, v5
	v_exp_f32_e32 v101, v5
	v_sub_f32_e32 v5, v150, v148
	v_mul_f32_e32 v5, 0x3fb8aa3b, v5
	v_exp_f32_e32 v104, v5
	v_sub_f32_e32 v5, v151, v148
	v_mul_f32_e32 v5, 0x3fb8aa3b, v5
	v_exp_f32_e32 v105, v5
	v_sub_f32_e32 v5, v152, v148
	v_mul_f32_e32 v5, 0x3fb8aa3b, v5
	v_exp_f32_e32 v102, v5
	v_sub_f32_e32 v5, v153, v148
	v_mul_f32_e32 v5, 0x3fb8aa3b, v5
	v_exp_f32_e32 v103, v5
	v_sub_f32_e32 v5, v154, v148
	v_mul_f32_e32 v5, 0x3fb8aa3b, v5
	v_exp_f32_e32 v110, v5
	v_sub_f32_e32 v5, v155, v148
	v_sub_f32_e32 v3, v148, v148
	v_mul_f32_e32 v5, 0x3fb8aa3b, v5
	v_mul_f32_e32 v3, 0x3fb8aa3b, v3
	v_exp_f32_e32 v111, v5
	v_sub_f32_e32 v5, v156, v148
	v_exp_f32_e32 v100, v3
	v_mul_f32_e32 v5, 0x3fb8aa3b, v5
	v_exp_f32_e32 v112, v5
	v_sub_f32_e32 v5, v157, v148
	v_mul_f32_e32 v5, 0x3fb8aa3b, v5
	v_exp_f32_e32 v113, v5
	v_sub_f32_e32 v5, v158, v148
	v_add_f32_e32 v3, 0, v100
	v_mul_f32_e32 v5, 0x3fb8aa3b, v5
	v_add_f32_e32 v3, v3, v101
	v_exp_f32_e32 v114, v5
	v_sub_f32_e32 v5, v159, v148
	v_add_f32_e32 v3, v3, v104
	v_mul_f32_e32 v5, 0x3fb8aa3b, v5
	v_add_f32_e32 v3, v3, v105
	v_exp_f32_e32 v115, v5
	v_sub_f32_e32 v5, v160, v148
	v_add_f32_e32 v3, v3, v102
	v_mul_f32_e32 v5, 0x3fb8aa3b, v5
	v_add_f32_e32 v3, v3, v103
	v_exp_f32_e32 v106, v5
	v_sub_f32_e32 v5, v161, v148
	v_add_f32_e32 v3, v3, v110
	v_mul_f32_e32 v5, 0x3fb8aa3b, v5
	v_add_f32_e32 v3, v3, v111
	v_exp_f32_e32 v107, v5
	v_sub_f32_e32 v5, v162, v148
	v_add_f32_e32 v3, v3, v112
	v_mul_f32_e32 v5, 0x3fb8aa3b, v5
	v_add_f32_e32 v3, v3, v113
	v_exp_f32_e32 v108, v5
	v_sub_f32_e32 v5, v163, v148
	v_add_f32_e32 v3, v3, v114
	v_mul_f32_e32 v5, 0x3fb8aa3b, v5
	v_add_f32_e32 v3, v3, v115
	v_exp_f32_e32 v109, v5
	v_add_f32_e32 v3, v3, v106
	v_add_f32_e32 v3, v3, v107
	v_add_f32_e32 v3, v3, v108
	v_add_f32_e32 v3, v3, v109
	v_div_scale_f32 v5, s[0:1], v3, v3, 1.0
	v_rcp_f32_e32 v6, v5
	v_ashrrev_i32_e32 v19, 31, v18
	s_mov_b32 s0, 0x10000
	v_lshlrev_b64 v[120:121], 9, v[18:19]
	v_fma_f32 v17, -v5, v6, 1.0
	v_fmac_f32_e32 v6, v17, v6
	v_div_scale_f32 v17, vcc, 1.0, v3, 1.0
	v_mul_f32_e32 v20, v17, v6
	v_fma_f32 v21, -v5, v20, v17
	v_fmac_f32_e32 v20, v21, v6
	v_fma_f32 v5, -v5, v20, v17
	v_div_fmas_f32 v5, v5, v6, v20
	v_div_fixup_f32 v116, v5, v3, 1.0
	v_bfe_u32 v3, v163, 4, 4
	v_and_b32_e32 v2, 15, v163
	v_and_b32_e32 v17, 15, v155
	v_add_u32_e32 v3, v138, v3
	v_add_u32_e32 v2, v138, v2
	v_add_u32_e32 v17, v138, v17
	ds_read_u8 v3, v3
	ds_read_u8 v17, v17 offset:16
	ds_read_u8 v2, v2 offset:16
	v_and_b32_e32 v6, 15, v160
	v_add_u32_e32 v6, v138, v6
	ds_read_u8 v6, v6 offset:16
	v_lshl_add_u64 v[18:19], s[8:9], 0, v[120:121]
	s_waitcnt lgkmcnt(1)
; DEV void phase_peer_score(const Params& p, int layer, int M, char* smem) {
;     ...
;     int eid[16];
; #pragma unroll
;     for (int t = 0; t < 16; t++) {
;       unsigned code = __float_as_uint(R[t]) & 255u;
;       eid[t] = (int)tab[code >> 4] * 128 + (int)tab[16 + (code & 15u)];
;     }
	v_lshl_add_u32 v5, v3, 7, v2
	v_bfe_u32 v2, v162, 4, 4
	v_and_b32_e32 v3, 15, v162
	v_add_u32_e32 v2, v138, v2
	v_add_u32_e32 v3, v138, v3
	ds_read_u8 v2, v2
	ds_read_u8 v3, v3 offset:16
	s_lshl_b32 s52, s19, 6
	v_lshl_add_u64 v[118:119], v[18:19], 0, s[52:53]
	v_lshl_add_u64 v[120:121], s[6:7], 0, v[120:121]
	v_lshl_add_u64 v[120:121], v[120:121], 0, s[52:53]
	s_waitcnt lgkmcnt(0)
	v_lshl_add_u32 v4, v2, 7, v3
	v_bfe_u32 v2, v161, 4, 4
	v_and_b32_e32 v3, 15, v161
	v_add_u32_e32 v2, v138, v2
	v_add_u32_e32 v3, v138, v3
	ds_read_u8 v2, v2
	ds_read_u8 v3, v3 offset:16
	v_and_b32_e32 v7, 15, v159
	v_add_u32_e32 v7, v138, v7
	ds_read_u8 v7, v7 offset:16
	s_waitcnt lgkmcnt(1)
	v_lshl_add_u32 v3, v2, 7, v3
	v_bfe_u32 v2, v160, 4, 4
	v_add_u32_e32 v2, v138, v2
	ds_read_u8 v2, v2
	s_waitcnt lgkmcnt(0)
	v_lshl_add_u32 v2, v2, 7, v6
	v_bfe_u32 v6, v159, 4, 4
	v_add_u32_e32 v6, v138, v6
	ds_read_u8 v6, v6
	s_waitcnt lgkmcnt(0)
	v_lshl_add_u32 v9, v6, 7, v7
	v_bfe_u32 v6, v158, 4, 4
	v_and_b32_e32 v7, 15, v158
	v_add_u32_e32 v6, v138, v6
	v_add_u32_e32 v7, v138, v7
	ds_read_u8 v6, v6
	ds_read_u8 v7, v7 offset:16
	s_waitcnt lgkmcnt(0)
	v_lshl_add_u32 v8, v6, 7, v7
	v_bfe_u32 v6, v157, 4, 4
	v_and_b32_e32 v7, 15, v157
	v_add_u32_e32 v6, v138, v6
	v_add_u32_e32 v7, v138, v7
	ds_read_u8 v6, v6
	ds_read_u8 v7, v7 offset:16
	s_waitcnt lgkmcnt(0)
	v_lshl_add_u32 v7, v6, 7, v7
	v_bfe_u32 v6, v156, 4, 4
	v_and_b32_e32 v13, 15, v156
	v_add_u32_e32 v6, v138, v6
	v_add_u32_e32 v13, v138, v13
	ds_read_u8 v6, v6
	ds_read_u8 v13, v13 offset:16
	s_waitcnt lgkmcnt(0)
	v_lshl_add_u32 v6, v6, 7, v13
	v_bfe_u32 v13, v155, 4, 4
	v_add_u32_e32 v13, v138, v13
	ds_read_u8 v13, v13
	s_waitcnt lgkmcnt(0)
	v_lshl_add_u32 v13, v13, 7, v17
	v_bfe_u32 v17, v154, 4, 4
	v_and_b32_e32 v12, 15, v154
	v_add_u32_e32 v17, v138, v17
	v_add_u32_e32 v12, v138, v12
	ds_read_u8 v17, v17
	ds_read_u8 v12, v12 offset:16
	s_waitcnt lgkmcnt(0)
	v_lshl_add_u32 v12, v17, 7, v12
	v_bfe_u32 v17, v153, 4, 4
	v_and_b32_e32 v11, 15, v153
	v_add_u32_e32 v17, v138, v17
	v_add_u32_e32 v11, v138, v11
	ds_read_u8 v17, v17
	ds_read_u8 v11, v11 offset:16
	s_waitcnt lgkmcnt(0)
	v_lshl_add_u32 v11, v17, 7, v11
	v_bfe_u32 v17, v152, 4, 4
	v_and_b32_e32 v10, 15, v152
	v_add_u32_e32 v17, v138, v17
	v_add_u32_e32 v10, v138, v10
	ds_read_u8 v17, v17
	ds_read_u8 v10, v10 offset:16
	s_waitcnt lgkmcnt(0)
	v_lshl_add_u32 v10, v17, 7, v10
	v_bfe_u32 v17, v151, 4, 4
	v_and_b32_e32 v16, 15, v151
	v_add_u32_e32 v17, v138, v17
	v_add_u32_e32 v16, v138, v16
	ds_read_u8 v17, v17
	ds_read_u8 v16, v16 offset:16
	s_waitcnt lgkmcnt(0)
	v_lshl_add_u32 v17, v17, 7, v16
	v_bfe_u32 v16, v150, 4, 4
	v_and_b32_e32 v15, 15, v150
	v_add_u32_e32 v16, v138, v16
	v_add_u32_e32 v15, v138, v15
	ds_read_u8 v16, v16
	ds_read_u8 v15, v15 offset:16
	s_waitcnt lgkmcnt(0)
	v_lshl_add_u32 v16, v16, 7, v15
	v_bfe_u32 v15, v149, 4, 4
	v_and_b32_e32 v14, 15, v149
	v_add_u32_e32 v15, v138, v15
	v_add_u32_e32 v14, v138, v14
	ds_read_u8 v15, v15
	ds_read_u8 v14, v14 offset:16
	s_waitcnt lgkmcnt(0)
	v_lshl_add_u32 v15, v15, 7, v14
	v_bfe_u32 v14, v148, 4, 4
	v_and_b32_e32 v0, 15, v148
	v_add_u32_e32 v14, v138, v14
	v_add_u32_e32 v0, v138, v0
	ds_read_u8 v14, v14
	ds_read_u8 v0, v0 offset:16
	s_waitcnt lgkmcnt(0)
; DEV void phase_peer_score(const Params& p, int layer, int M, char* smem) {
;     ...
;     if (quad == 0) {
;       int* eo = EIDX + (size_t)m * 128 + h * 16;
;       float* go = GATE + (size_t)m * 128 + h * 16;
;       float* uo = go + (size_t)MT * 128;
;       float us[16], vs[16];
; #pragma unroll
;       for (int t = 0; t < 16; t++) { us[t] = USC[eid[t]]; vs[t] = USC[16384 + eid[t]]; }
; #pragma unroll
;       for (int t = 0; t < 16; t += 4) {
;         *(int4*)(eo + t) = make_int4(eid[t], eid[t + 1], eid[t + 2], eid[t + 3]);
;         *(float4*)(go + t) = make_float4(ev[t] * inv * vs[t], ev[t + 1] * inv * vs[t + 1], ev[t + 2] * inv * vs[t + 2], ev[t + 3] * inv * vs[t + 3]);
;         *(float4*)(uo + t) = make_float4(us[t], us[t + 1], us[t + 2], us[t + 3]);
;       }
	v_lshl_add_u32 v14, v14, 7, v0
	v_lshlrev_b32_e32 v0, 2, v14
	v_lshl_add_u64 v[20:21], s[10:11], 0, v[0:1]
	v_add_co_u32_e32 v20, vcc, s0, v20
	global_load_dword v18, v0, s[10:11]
	s_nop 0
	v_addc_co_u32_e32 v21, vcc, 0, v21, vcc
	global_load_dword v122, v[20:21], off
	v_lshlrev_b32_e32 v0, 2, v15
	v_lshl_add_u64 v[20:21], s[10:11], 0, v[0:1]
	v_add_co_u32_e32 v20, vcc, s0, v20
	global_load_dword v19, v0, s[10:11]
	s_nop 0
	v_addc_co_u32_e32 v21, vcc, 0, v21, vcc
	global_load_dword v123, v[20:21], off
	v_lshlrev_b32_e32 v0, 2, v16
	v_lshl_add_u64 v[22:23], s[10:11], 0, v[0:1]
	v_add_co_u32_e32 v22, vcc, s0, v22
	global_load_dword v20, v0, s[10:11]
	s_nop 0
	v_addc_co_u32_e32 v23, vcc, 0, v23, vcc
	global_load_dword v126, v[22:23], off
	v_lshlrev_b32_e32 v0, 2, v17
	v_lshl_add_u64 v[22:23], s[10:11], 0, v[0:1]
	v_add_co_u32_e32 v22, vcc, s0, v22
	global_load_dword v21, v0, s[10:11]
	s_nop 0
	v_addc_co_u32_e32 v23, vcc, 0, v23, vcc
	global_load_dword v127, v[22:23], off
	v_lshlrev_b32_e32 v0, 2, v10
	v_lshl_add_u64 v[24:25], s[10:11], 0, v[0:1]
	v_add_co_u32_e32 v24, vcc, s0, v24
	global_load_dword v22, v0, s[10:11]
	s_nop 0
	v_addc_co_u32_e32 v25, vcc, 0, v25, vcc
	global_load_dword v124, v[24:25], off
	v_lshlrev_b32_e32 v0, 2, v11
	v_lshl_add_u64 v[24:25], s[10:11], 0, v[0:1]
	v_add_co_u32_e32 v24, vcc, s0, v24
	global_load_dword v23, v0, s[10:11]
	s_nop 0
	v_addc_co_u32_e32 v25, vcc, 0, v25, vcc
	global_load_dword v125, v[24:25], off
	v_lshlrev_b32_e32 v0, 2, v12
	v_lshl_add_u64 v[26:27], s[10:11], 0, v[0:1]
	v_add_co_u32_e32 v26, vcc, s0, v26
	global_load_dword v24, v0, s[10:11]
	s_nop 0
	v_addc_co_u32_e32 v27, vcc, 0, v27, vcc
	global_load_dword v128, v[26:27], off
	v_lshlrev_b32_e32 v0, 2, v13
	v_lshl_add_u64 v[26:27], s[10:11], 0, v[0:1]
	v_add_co_u32_e32 v26, vcc, s0, v26
	global_load_dword v25, v0, s[10:11]
	s_nop 0
	v_addc_co_u32_e32 v27, vcc, 0, v27, vcc
	global_load_dword v129, v[26:27], off
	v_lshlrev_b32_e32 v0, 2, v6
	v_lshl_add_u64 v[28:29], s[10:11], 0, v[0:1]
	v_add_co_u32_e32 v28, vcc, s0, v28
	global_load_dword v26, v0, s[10:11]
	s_nop 0
	v_addc_co_u32_e32 v29, vcc, 0, v29, vcc
	global_load_dword v130, v[28:29], off
	v_lshlrev_b32_e32 v0, 2, v7
	v_lshl_add_u64 v[28:29], s[10:11], 0, v[0:1]
	v_add_co_u32_e32 v28, vcc, s0, v28
	global_load_dword v27, v0, s[10:11]
	s_nop 0
	v_addc_co_u32_e32 v29, vcc, 0, v29, vcc
	global_load_dword v131, v[28:29], off
	v_lshlrev_b32_e32 v0, 2, v8
	v_lshl_add_u64 v[30:31], s[10:11], 0, v[0:1]
	v_add_co_u32_e32 v30, vcc, s0, v30
	global_load_dword v28, v0, s[10:11]
	s_nop 0
	v_addc_co_u32_e32 v31, vcc, 0, v31, vcc
	global_load_dword v132, v[30:31], off
	v_lshlrev_b32_e32 v0, 2, v9
	v_lshl_add_u64 v[30:31], s[10:11], 0, v[0:1]
	v_add_co_u32_e32 v30, vcc, s0, v30
	global_load_dword v29, v0, s[10:11]
	s_nop 0
	v_addc_co_u32_e32 v31, vcc, 0, v31, vcc
	global_load_dword v133, v[30:31], off
	v_lshlrev_b32_e32 v0, 2, v2
	v_lshl_add_u64 v[32:33], s[10:11], 0, v[0:1]
	v_add_co_u32_e32 v32, vcc, s0, v32
	global_load_dword v30, v0, s[10:11]
	s_nop 0
	v_addc_co_u32_e32 v33, vcc, 0, v33, vcc
	global_load_dword v134, v[32:33], off
	v_lshlrev_b32_e32 v0, 2, v3
	v_lshl_add_u64 v[32:33], s[10:11], 0, v[0:1]
	v_add_co_u32_e32 v32, vcc, s0, v32
	global_load_dword v31, v0, s[10:11]
	s_nop 0
	v_addc_co_u32_e32 v33, vcc, 0, v33, vcc
	global_load_dword v135, v[32:33], off
	v_lshlrev_b32_e32 v0, 2, v4
	v_lshl_add_u64 v[136:137], s[10:11], 0, v[0:1]
	v_add_co_u32_e32 v136, vcc, s0, v136
	global_load_dword v32, v0, s[10:11]
	s_nop 0
	v_addc_co_u32_e32 v137, vcc, 0, v137, vcc
	global_load_dword v136, v[136:137], off
	v_lshlrev_b32_e32 v0, 2, v5
	v_lshl_add_u64 v[140:141], s[10:11], 0, v[0:1]
	v_add_co_u32_e32 v140, vcc, s0, v140
	global_load_dword v33, v0, s[10:11]
	s_nop 0
	v_addc_co_u32_e32 v141, vcc, 0, v141, vcc
	global_load_dword v137, v[140:141], off
	s_mov_b32 s0, 0x840000
	global_store_dwordx4 v[120:121], v[14:17], off
	s_nop 1
	v_pk_mul_f32 v[14:15], v[100:101], v[116:117] op_sel_hi:[1,0]
	v_pk_mul_f32 v[16:17], v[104:105], v[116:117] op_sel_hi:[1,0]
	s_waitcnt vmcnt(29)
	v_pk_mul_f32 v[14:15], v[14:15], v[122:123]
	s_waitcnt vmcnt(25)
	v_pk_mul_f32 v[16:17], v[16:17], v[126:127]
	global_store_dwordx4 v[118:119], v[14:17], off
	s_nop 1
	v_add_co_u32_e32 v14, vcc, s0, v118
	s_nop 1
	v_addc_co_u32_e32 v15, vcc, 0, v119, vcc
	global_store_dwordx4 v[14:15], v[18:21], off
	global_store_dwordx4 v[120:121], v[10:13], off offset:16
	s_nop 1
	v_pk_mul_f32 v[10:11], v[102:103], v[116:117] op_sel_hi:[1,0]
	v_pk_mul_f32 v[12:13], v[110:111], v[116:117] op_sel_hi:[1,0]
	s_waitcnt vmcnt(24)
	v_pk_mul_f32 v[10:11], v[10:11], v[124:125]
	s_waitcnt vmcnt(20)
	v_pk_mul_f32 v[12:13], v[12:13], v[128:129]
	global_store_dwordx4 v[118:119], v[10:13], off offset:16
	global_store_dwordx4 v[14:15], v[22:25], off offset:16
	global_store_dwordx4 v[120:121], v[6:9], off offset:32
	s_nop 1
	v_pk_mul_f32 v[6:7], v[112:113], v[116:117] op_sel_hi:[1,0]
	v_pk_mul_f32 v[8:9], v[114:115], v[116:117] op_sel_hi:[1,0]
	s_waitcnt vmcnt(19)
	v_pk_mul_f32 v[6:7], v[6:7], v[130:131]
	s_waitcnt vmcnt(15)
	v_pk_mul_f32 v[8:9], v[8:9], v[132:133]
	global_store_dwordx4 v[118:119], v[6:9], off offset:32
	global_store_dwordx4 v[14:15], v[26:29], off offset:32
	global_store_dwordx4 v[120:121], v[2:5], off offset:48
	s_nop 1
	v_pk_mul_f32 v[2:3], v[106:107], v[116:117] op_sel_hi:[1,0]
	v_pk_mul_f32 v[4:5], v[108:109], v[116:117] op_sel_hi:[1,0]
	s_waitcnt vmcnt(14)
	v_pk_mul_f32 v[2:3], v[2:3], v[134:135]
	s_waitcnt vmcnt(10)
	v_pk_mul_f32 v[4:5], v[4:5], v[136:137]
	global_store_dwordx4 v[118:119], v[2:5], off offset:48
	global_store_dwordx4 v[14:15], v[30:33], off offset:48
	s_branch .LBB0_162

; DEV f32x4 mfma16(bf16x8 a, bf16x8 b, f32x4 c) { return __builtin_amdgcn_mfma_f32_16x16x32_bf16(a, b, c, 0, 0, 0); }
; DEV void peer_top16(const bf16_t* __restrict__ pq, const bf16_t* sk  , float (&l)[16]) {
;     ...
; #pragma unroll 1
;   for (int ks = 0; ks < 4; ks++) {
;     const bf16x8 bqk = *(const bf16x8*)(pq + ks * 32 + quad * 8);
; #pragma unroll
;     for (int nt = 0; nt < 8; nt++) {
;       bf16x8 ak = *(const bf16x8*)(sk + (nt * 16 + l15) * 144 + ks * 32 + quad * 8);
;       acc[nt] = mfma16(ak, bqk, acc[nt]);
;     }
;   }
.LBB0_635:
	v_add_u32_e32 v139, 0x10e00, v122
	ds_read_b128 v[164:167], v122 offset:36864
	ds_read_b128 v[168:171], v122 offset:41472
	ds_read_b128 v[172:175], v122 offset:46080
	ds_read_b128 v[176:179], v122 offset:50688
	ds_read_b128 v[180:183], v122 offset:55296
	ds_read_b128 v[184:187], v122 offset:59904
	ds_read_b128 v[188:191], v122 offset:64512
	ds_read_b128 v[128:131], v139
	s_waitcnt vmcnt(3) lgkmcnt(7)
	v_mfma_f32_16x16x32_bf16 v[30:33], v[164:167], v[148:151], v[30:33]
	ds_read_b128 v[164:167], v122 offset:36928
	s_waitcnt lgkmcnt(7)
	v_mfma_f32_16x16x32_bf16 v[22:25], v[168:171], v[148:151], v[22:25]
	ds_read_b128 v[168:171], v122 offset:41536
	s_waitcnt lgkmcnt(7)
	v_mfma_f32_16x16x32_bf16 v[14:17], v[172:175], v[148:151], v[14:17]
	ds_read_b128 v[172:175], v122 offset:46144
	s_waitcnt lgkmcnt(7)
	v_mfma_f32_16x16x32_bf16 v[6:9], v[176:179], v[148:151], v[6:9]
	ds_read_b128 v[176:179], v122 offset:50752
	s_waitcnt lgkmcnt(7)
	v_mfma_f32_16x16x32_bf16 v[26:29], v[180:183], v[148:151], v[26:29]
	ds_read_b128 v[180:183], v122 offset:55360
	s_waitcnt lgkmcnt(7)
	v_mfma_f32_16x16x32_bf16 v[18:21], v[184:187], v[148:151], v[18:21]
	ds_read_b128 v[184:187], v122 offset:59968
	s_waitcnt lgkmcnt(7)
	v_mfma_f32_16x16x32_bf16 v[10:13], v[188:191], v[148:151], v[10:13]
	ds_read_b128 v[188:191], v122 offset:64576
	s_waitcnt lgkmcnt(7)
	v_mfma_f32_16x16x32_bf16 v[2:5], v[128:131], v[148:151], v[2:5]
	ds_read_b128 v[128:131], v139 offset:64
	s_waitcnt vmcnt(2) lgkmcnt(7)
	v_mfma_f32_16x16x32_bf16 v[30:33], v[164:167], v[152:155], v[30:33]
	ds_read_b128 v[164:167], v122 offset:36992
	s_waitcnt lgkmcnt(7)
	v_mfma_f32_16x16x32_bf16 v[22:25], v[168:171], v[152:155], v[22:25]
	ds_read_b128 v[168:171], v122 offset:41600
	s_waitcnt lgkmcnt(7)
	v_mfma_f32_16x16x32_bf16 v[14:17], v[172:175], v[152:155], v[14:17]
	ds_read_b128 v[172:175], v122 offset:46208
	s_waitcnt lgkmcnt(7)
	v_mfma_f32_16x16x32_bf16 v[6:9], v[176:179], v[152:155], v[6:9]
	ds_read_b128 v[176:179], v122 offset:50816
	s_waitcnt lgkmcnt(7)
	v_mfma_f32_16x16x32_bf16 v[26:29], v[180:183], v[152:155], v[26:29]
	ds_read_b128 v[180:183], v122 offset:55424
	s_waitcnt lgkmcnt(7)
	v_mfma_f32_16x16x32_bf16 v[18:21], v[184:187], v[152:155], v[18:21]
	ds_read_b128 v[184:187], v122 offset:60032
	s_waitcnt lgkmcnt(7)
	v_mfma_f32_16x16x32_bf16 v[10:13], v[188:191], v[152:155], v[10:13]
	ds_read_b128 v[188:191], v122 offset:64640
	s_waitcnt lgkmcnt(7)
	v_mfma_f32_16x16x32_bf16 v[2:5], v[128:131], v[152:155], v[2:5]
	ds_read_b128 v[128:131], v139 offset:128
	s_waitcnt vmcnt(1) lgkmcnt(7)
	v_mfma_f32_16x16x32_bf16 v[30:33], v[164:167], v[156:159], v[30:33]
	ds_read_b128 v[164:167], v122 offset:37056
	s_waitcnt lgkmcnt(7)
	v_mfma_f32_16x16x32_bf16 v[22:25], v[168:171], v[156:159], v[22:25]
	ds_read_b128 v[168:171], v122 offset:41664
	s_waitcnt lgkmcnt(7)
	v_mfma_f32_16x16x32_bf16 v[14:17], v[172:175], v[156:159], v[14:17]
	ds_read_b128 v[172:175], v122 offset:46272
	s_waitcnt lgkmcnt(7)
	v_mfma_f32_16x16x32_bf16 v[6:9], v[176:179], v[156:159], v[6:9]
	ds_read_b128 v[176:179], v122 offset:50880
	s_waitcnt lgkmcnt(7)
	v_mfma_f32_16x16x32_bf16 v[26:29], v[180:183], v[156:159], v[26:29]
	ds_read_b128 v[180:183], v122 offset:55488
	s_waitcnt lgkmcnt(7)
	v_mfma_f32_16x16x32_bf16 v[18:21], v[184:187], v[156:159], v[18:21]
	ds_read_b128 v[184:187], v122 offset:60096
	s_waitcnt lgkmcnt(7)
	v_mfma_f32_16x16x32_bf16 v[10:13], v[188:191], v[156:159], v[10:13]
	ds_read_b128 v[188:191], v122 offset:64704
	s_waitcnt lgkmcnt(7)
	v_mfma_f32_16x16x32_bf16 v[2:5], v[128:131], v[156:159], v[2:5]
	ds_read_b128 v[128:131], v139 offset:192
	s_waitcnt vmcnt(0) lgkmcnt(7)
	v_mfma_f32_16x16x32_bf16 v[30:33], v[164:167], v[160:163], v[30:33]
	s_waitcnt lgkmcnt(6)
	v_mfma_f32_16x16x32_bf16 v[22:25], v[168:171], v[160:163], v[22:25]
	s_waitcnt lgkmcnt(5)
	v_mfma_f32_16x16x32_bf16 v[14:17], v[172:175], v[160:163], v[14:17]
	s_waitcnt lgkmcnt(4)
	v_mfma_f32_16x16x32_bf16 v[6:9], v[176:179], v[160:163], v[6:9]
	s_waitcnt lgkmcnt(3)
	v_mfma_f32_16x16x32_bf16 v[26:29], v[180:183], v[160:163], v[26:29]
	s_waitcnt lgkmcnt(2)
	v_mfma_f32_16x16x32_bf16 v[18:21], v[184:187], v[160:163], v[18:21]
	s_waitcnt lgkmcnt(1)
	v_mfma_f32_16x16x32_bf16 v[10:13], v[188:191], v[160:163], v[10:13]
	s_waitcnt lgkmcnt(0)
; DEV void peer_top16(const bf16_t* __restrict__ pq, const bf16_t* sk  , float (&l)[16]) {
;     ...
;   float hi[16];
; #pragma unroll
;   for (int nt = 0; nt < 4; nt++)
; #pragma unroll
;     for (int r = 0; r < 4; r++) {
;       l[nt * 4 + r] = __uint_as_float((__float_as_uint(acc[nt][r]) & ~127u) | (unsigned)(nt * 16 + quad * 4 + r));
;       hi[nt * 4 + r] = __uint_as_float((__float_as_uint(acc[nt + 4][r]) & ~127u) | (unsigned)((nt + 4) * 16 + quad * 4 + r));
;     }
;   sort16_desc(l);
;   sort16_desc(hi);
; #pragma unroll
;   for (int i = 0; i < 16; i++) l[i] = fmaxf(l[i], hi[15 - i]);
;   bitonic16(l);
	v_mfma_f32_16x16x32_bf16 v[2:5], v[128:131], v[160:163], v[2:5]
	s_movk_i32 s18, 0x100
	v_max_f32_e32 v0, v109, v121
	v_max_f32_e32 v100, v107, v120
	v_max_f32_e32 v101, v105, v119
	v_max_f32_e32 v103, v103, v118
	v_max_f32_e32 v87, v87, v116
	v_max_f32_e32 v79, v79, v115
	v_max_f32_e32 v75, v75, v114
	v_max_f32_e32 v71, v71, v113
	v_max_f32_e32 v67, v67, v112
	v_max_f32_e32 v63, v63, v111
	v_max_f32_e32 v59, v59, v110
	v_max_f32_e32 v55, v55, v108
	v_max_f32_e32 v51, v51, v106
	v_max_f32_e32 v47, v47, v104
	v_max_f32_e32 v43, v43, v91
	v_max_f32_e32 v39, v39, v83
	v_max_f32_e32 v83, v0, v67
	v_min_f32_e32 v0, v0, v67
	v_max_f32_e32 v67, v100, v63
	v_min_f32_e32 v63, v100, v63
	v_max_f32_e32 v91, v101, v59
	v_min_f32_e32 v59, v101, v59
	v_max_f32_e32 v100, v103, v55
	v_min_f32_e32 v55, v103, v55
	v_max_f32_e32 v101, v87, v51
	v_min_f32_e32 v51, v87, v51
	v_max_f32_e32 v87, v79, v47
	v_min_f32_e32 v47, v79, v47
	v_max_f32_e32 v79, v75, v43
	v_min_f32_e32 v43, v75, v43
	v_max_f32_e32 v75, v71, v39
	v_min_f32_e32 v39, v71, v39
	v_max_f32_e32 v71, v83, v101
	v_min_f32_e32 v101, v83, v101
	v_max_f32_e32 v103, v67, v87
	v_min_f32_e32 v67, v67, v87
	v_max_f32_e32 v87, v91, v79
	v_min_f32_e32 v79, v91, v79
	v_max_f32_e32 v91, v100, v75
	v_min_f32_e32 v75, v100, v75
	v_max_f32_e32 v100, v0, v51
	v_min_f32_e32 v0, v0, v51
	v_max_f32_e32 v51, v63, v47
	v_max_f32_e32 v105, v59, v43
	v_min_f32_e32 v43, v59, v43
	v_max_f32_e32 v59, v55, v39
	v_min_f32_e32 v107, v101, v79
	v_min_f32_e32 v108, v67, v75
	v_min_f32_e32 v110, v51, v59
	v_max_f32_e32 v79, v101, v79
	v_max_f32_e32 v67, v67, v75
	v_max_f32_e32 v101, v100, v105
	v_max_f32_e32 v51, v51, v59
	v_min_f32_e32 v75, v79, v67
	v_min_f32_e32 v59, v101, v51
	v_max_f32_e32 v79, v79, v67
	v_max_f32_e32 v67, v101, v51
	v_lshlrev_b32_e32 v101, 2, v102
	s_movk_i32 s8, 0xff80
	v_and_or_b32 v30, v30, s8, v101
	v_and_b32_e32 v27, 0xffffff80, v27
	s_movk_i32 s8, 0x41
	v_or3_b32 v27, v101, v27, s8
	v_and_b32_e32 v28, 0xffffff80, v28
	s_movk_i32 s8, 0x42
	v_or3_b32 v28, v101, v28, s8
	v_and_b32_e32 v29, 0xffffff80, v29
	s_movk_i32 s8, 0x43
	v_or3_b32 v29, v101, v29, s8
	v_and_b32_e32 v18, 0xffffff80, v18
	s_movk_i32 s8, 0x50
	v_or3_b32 v18, v101, v18, s8
	v_and_b32_e32 v19, 0xffffff80, v19
	s_movk_i32 s8, 0x51
	v_or3_b32 v19, v101, v19, s8
	v_and_b32_e32 v20, 0xffffff80, v20
	s_movk_i32 s8, 0x52
	v_or3_b32 v20, v101, v20, s8
	v_and_b32_e32 v21, 0xffffff80, v21
	s_movk_i32 s8, 0x53
	v_or3_b32 v21, v101, v21, s8
	v_and_b32_e32 v10, 0xffffff80, v10
	s_movk_i32 s8, 0x60
	v_or3_b32 v10, v101, v10, s8
	v_and_b32_e32 v11, 0xffffff80, v11
	s_movk_i32 s8, 0x61
	v_or3_b32 v11, v101, v11, s8
	v_and_b32_e32 v12, 0xffffff80, v12
	s_movk_i32 s8, 0x62
	v_or3_b32 v12, v101, v12, s8
	v_and_b32_e32 v13, 0xffffff80, v13
	s_movk_i32 s8, 0x63
	v_or3_b32 v13, v101, v13, s8
	v_and_b32_e32 v2, 0xffffff80, v2
	s_movk_i32 s8, 0x70
	v_and_b32_e32 v26, 0xffffff80, v26
	v_and_b32_e32 v31, 0xffffff80, v31
	v_or3_b32 v2, v101, v2, s8
	v_and_b32_e32 v3, 0xffffff80, v3
	s_movk_i32 s8, 0x71
	v_or3_b32 v26, v101, v26, 64
	v_or3_b32 v31, v101, v31, 1
	v_and_b32_e32 v32, 0xffffff80, v32
	v_and_b32_e32 v33, 0xffffff80, v33
	v_and_b32_e32 v22, 0xffffff80, v22
	v_and_b32_e32 v23, 0xffffff80, v23
	v_or3_b32 v3, v101, v3, s8
	v_and_b32_e32 v4, 0xffffff80, v4
	s_movk_i32 s8, 0x72
	v_min_f32_e32 v39, v55, v39
	v_min_f32_e32 v55, v71, v87
	v_min_f32_e32 v106, v103, v91
	v_min_f32_e32 v109, v100, v105
	v_max_f32_e32 v71, v71, v87
	v_max_f32_e32 v87, v103, v91
	v_or3_b32 v32, v101, v32, 2
	v_or3_b32 v33, v101, v33, 3
	v_or3_b32 v22, v101, v22, 16
	v_or3_b32 v23, v101, v23, 17
	v_and_b32_e32 v24, 0xffffff80, v24
	v_and_b32_e32 v25, 0xffffff80, v25
	v_and_b32_e32 v14, 0xffffff80, v14
	v_and_b32_e32 v15, 0xffffff80, v15
	v_and_b32_e32 v16, 0xffffff80, v16
	v_and_b32_e32 v17, 0xffffff80, v17
	v_and_b32_e32 v6, 0xffffff80, v6
	v_and_b32_e32 v7, 0xffffff80, v7
	v_and_b32_e32 v8, 0xffffff80, v8
	v_or3_b32 v4, v101, v4, s8
	v_and_b32_e32 v9, 0xffffff80, v9
	v_and_b32_e32 v5, 0xffffff80, v5
	s_movk_i32 s8, 0x73
	v_min_f32_e32 v104, v63, v47
	v_min_f32_e32 v83, v55, v106
	v_min_f32_e32 v47, v109, v110
	v_min_f32_e32 v91, v71, v87
	v_max_f32_e32 v100, v71, v87
	v_max_f32_e32 v87, v55, v106
	v_max_f32_e32 v55, v109, v110
	v_or3_b32 v24, v101, v24, 18
	v_or3_b32 v25, v101, v25, 19
	v_or3_b32 v14, v101, v14, 32
	v_or3_b32 v15, v101, v15, 33
	v_or3_b32 v16, v101, v16, 34
	v_or3_b32 v17, v101, v17, 35
	v_or3_b32 v6, v101, v6, 48
	v_or3_b32 v7, v101, v7, 49
	v_or3_b32 v8, v101, v8, 50
	v_or3_b32 v9, v101, v9, 51
	v_or3_b32 v5, v101, v5, s8
	v_max_f32_e32 v101, v30, v31
	v_min_f32_e32 v30, v30, v31
	v_max_f32_e32 v31, v32, v32
	v_max_f32_e32 v32, v33, v33
	v_max_f32_e32 v109, v26, v27
	v_min_f32_e32 v26, v26, v27
	v_max_f32_e32 v27, v28, v28
	v_max_f32_e32 v28, v29, v29
	v_max_f32_e32 v33, v32, v31
	v_min_f32_e32 v31, v32, v31
	v_max_f32_e32 v32, v22, v23
	v_min_f32_e32 v22, v22, v23
	v_max_f32_e32 v23, v24, v24
	v_max_f32_e32 v24, v25, v25
	v_max_f32_e32 v29, v28, v27
	v_min_f32_e32 v27, v28, v27
	v_max_f32_e32 v28, v18, v19
	v_min_f32_e32 v18, v18, v19
	v_max_f32_e32 v19, v20, v20
	v_max_f32_e32 v20, v21, v21
	v_max_f32_e32 v25, v24, v23
	v_min_f32_e32 v23, v24, v23
	v_max_f32_e32 v24, v14, v15
	v_min_f32_e32 v14, v14, v15
	v_max_f32_e32 v15, v16, v16
	v_max_f32_e32 v16, v17, v17
	v_max_f32_e32 v21, v20, v19
	v_min_f32_e32 v19, v20, v19
	v_max_f32_e32 v20, v10, v11
	v_min_f32_e32 v10, v10, v11
	v_max_f32_e32 v11, v12, v12
	v_max_f32_e32 v12, v13, v13
	v_max_f32_e32 v17, v16, v15
	v_min_f32_e32 v15, v16, v15
	v_max_f32_e32 v16, v6, v7
	v_min_f32_e32 v6, v6, v7
; DEV void ce(float& a, float& b) { float hi = fmaxf(a, b), lo = fminf(a, b); a = hi; b = lo; }
; DEV void sort16_desc(float (&a)[16]) {
; #pragma unroll
;   for (int k = 2; k <= 16; k <<= 1)
; #pragma unroll
;     for (int j = k >> 1; j > 0; j >>= 1)
; #pragma unroll
;       for (int i = 0; i < 16; i++) {
;         const int p = i ^ j;
;         if (p > i) { if ((i & k) == 0) ce(a[i], a[p]); else ce(a[p], a[i]); }
;       }
; }
	v_max_f32_e32 v7, v8, v8
	v_max_f32_e32 v8, v9, v9
	v_max_f32_e32 v13, v12, v11
	v_min_f32_e32 v11, v12, v11
	v_max_f32_e32 v12, v2, v3
	v_min_f32_e32 v2, v2, v3
	v_max_f32_e32 v3, v4, v4
	v_max_f32_e32 v4, v5, v5
	v_max_f32_e32 v9, v8, v7
	v_min_f32_e32 v7, v8, v7
	v_max_f32_e32 v5, v4, v3
	v_min_f32_e32 v3, v4, v3
	v_max_f32_e32 v8, v101, v31
	v_min_f32_e32 v31, v101, v31
	v_max_f32_e32 v101, v30, v33
	v_min_f32_e32 v30, v30, v33
	v_max_f32_e32 v33, v23, v32
	v_min_f32_e32 v23, v23, v32
	v_max_f32_e32 v32, v25, v22
	v_min_f32_e32 v22, v25, v22
	v_max_f32_e32 v25, v24, v15
	v_min_f32_e32 v15, v24, v15
	v_max_f32_e32 v24, v14, v17
	v_min_f32_e32 v14, v14, v17
	v_max_f32_e32 v17, v7, v16
	v_min_f32_e32 v7, v7, v16
	v_max_f32_e32 v16, v9, v6
	v_min_f32_e32 v6, v9, v6
	v_max_f32_e32 v4, v109, v27
	v_min_f32_e32 v27, v109, v27
	v_max_f32_e32 v109, v26, v29
	v_min_f32_e32 v26, v26, v29
	v_max_f32_e32 v29, v19, v28
	v_min_f32_e32 v19, v19, v28
	v_max_f32_e32 v28, v21, v18
	v_min_f32_e32 v18, v21, v18
	v_max_f32_e32 v21, v20, v11
	v_min_f32_e32 v11, v20, v11
	v_max_f32_e32 v20, v10, v13
	v_min_f32_e32 v10, v10, v13
	v_max_f32_e32 v13, v3, v12
	v_min_f32_e32 v3, v3, v12
	v_max_f32_e32 v12, v5, v2
	v_min_f32_e32 v2, v5, v2
	v_max_f32_e32 v9, v8, v101
	v_min_f32_e32 v8, v8, v101
	v_max_f32_e32 v101, v31, v30
	v_min_f32_e32 v30, v31, v30
	v_max_f32_e32 v31, v22, v23
	v_min_f32_e32 v22, v22, v23
	v_max_f32_e32 v23, v32, v33
	v_min_f32_e32 v32, v32, v33
	v_max_f32_e32 v33, v25, v24
	v_min_f32_e32 v24, v25, v24
	v_max_f32_e32 v25, v15, v14
	v_min_f32_e32 v14, v15, v14
	v_max_f32_e32 v15, v6, v7
	v_min_f32_e32 v6, v6, v7
	v_max_f32_e32 v7, v16, v17
	v_min_f32_e32 v16, v16, v17
	v_max_f32_e32 v5, v4, v109
	v_min_f32_e32 v4, v4, v109
	v_max_f32_e32 v109, v27, v26
	v_min_f32_e32 v26, v27, v26
	v_max_f32_e32 v27, v18, v19
	v_min_f32_e32 v18, v18, v19
	v_max_f32_e32 v19, v28, v29
	v_min_f32_e32 v28, v28, v29
	v_max_f32_e32 v29, v21, v20
	v_min_f32_e32 v20, v21, v20
	v_max_f32_e32 v21, v11, v10
	v_min_f32_e32 v10, v11, v10
	v_max_f32_e32 v11, v2, v3
	v_min_f32_e32 v2, v2, v3
	v_max_f32_e32 v3, v12, v13
	v_min_f32_e32 v12, v12, v13
	v_max_f32_e32 v17, v9, v22
	v_min_f32_e32 v9, v9, v22
	v_max_f32_e32 v22, v8, v31
	v_min_f32_e32 v8, v8, v31
	v_max_f32_e32 v31, v101, v32
	v_min_f32_e32 v32, v101, v32
	v_max_f32_e32 v101, v30, v23
	v_min_f32_e32 v23, v30, v23
	v_max_f32_e32 v30, v6, v33
	v_min_f32_e32 v6, v6, v33
	v_max_f32_e32 v33, v15, v24
	v_min_f32_e32 v15, v15, v24
	v_max_f32_e32 v24, v16, v25
	v_min_f32_e32 v16, v16, v25
	v_max_f32_e32 v25, v7, v14
	v_min_f32_e32 v7, v7, v14
	v_max_f32_e32 v13, v5, v18
	v_min_f32_e32 v5, v5, v18
	v_max_f32_e32 v18, v4, v27
	v_min_f32_e32 v4, v4, v27
	v_max_f32_e32 v27, v109, v28
	v_min_f32_e32 v28, v109, v28
	v_max_f32_e32 v109, v26, v19
	v_min_f32_e32 v19, v26, v19
	v_max_f32_e32 v26, v2, v29
	v_min_f32_e32 v2, v2, v29
	v_max_f32_e32 v29, v11, v20
	v_min_f32_e32 v11, v11, v20
	v_max_f32_e32 v20, v12, v21
	v_min_f32_e32 v12, v12, v21
	v_max_f32_e32 v21, v3, v10
	v_min_f32_e32 v3, v3, v10
	v_max_f32_e32 v14, v17, v31
	v_min_f32_e32 v17, v17, v31
	v_max_f32_e32 v31, v22, v101
	v_min_f32_e32 v22, v22, v101
	v_max_f32_e32 v101, v9, v32
	v_min_f32_e32 v9, v9, v32
	v_max_f32_e32 v32, v8, v23
	v_min_f32_e32 v8, v8, v23
	v_max_f32_e32 v23, v16, v6
	v_min_f32_e32 v6, v16, v6
	v_max_f32_e32 v16, v7, v15
	v_min_f32_e32 v7, v7, v15
	v_max_f32_e32 v15, v24, v30
	v_min_f32_e32 v24, v24, v30
	v_max_f32_e32 v30, v25, v33
	v_min_f32_e32 v25, v25, v33
	v_max_f32_e32 v10, v13, v27
	v_min_f32_e32 v13, v13, v27
	v_max_f32_e32 v27, v18, v109
	v_min_f32_e32 v18, v18, v109
	v_max_f32_e32 v109, v5, v28
	v_min_f32_e32 v5, v5, v28
	v_max_f32_e32 v28, v4, v19
	v_min_f32_e32 v4, v4, v19
	v_max_f32_e32 v19, v12, v2
	v_min_f32_e32 v2, v12, v2
	v_max_f32_e32 v12, v3, v11
	v_min_f32_e32 v3, v3, v11
	v_max_f32_e32 v11, v20, v26
	v_min_f32_e32 v20, v20, v26
	v_max_f32_e32 v26, v21, v29
	v_min_f32_e32 v21, v21, v29
	v_max_f32_e32 v33, v14, v31
	v_min_f32_e32 v14, v14, v31
	v_max_f32_e32 v31, v17, v22
	v_min_f32_e32 v17, v17, v22
	v_max_f32_e32 v22, v101, v32
	v_min_f32_e32 v32, v101, v32
	v_max_f32_e32 v101, v9, v8
	v_min_f32_e32 v8, v9, v8
	v_max_f32_e32 v9, v7, v6
	v_min_f32_e32 v6, v7, v6
	v_max_f32_e32 v7, v16, v23
	v_min_f32_e32 v16, v16, v23
	v_max_f32_e32 v23, v25, v24
	v_min_f32_e32 v24, v25, v24
	v_max_f32_e32 v25, v30, v15
	v_min_f32_e32 v15, v30, v15
	v_max_f32_e32 v29, v10, v27
	v_min_f32_e32 v10, v10, v27
	v_max_f32_e32 v27, v13, v18
	v_min_f32_e32 v13, v13, v18
	v_max_f32_e32 v18, v109, v28
	v_min_f32_e32 v28, v109, v28
	v_max_f32_e32 v109, v5, v4
	v_min_f32_e32 v4, v5, v4
	v_max_f32_e32 v5, v3, v2
	v_min_f32_e32 v2, v3, v2
	v_max_f32_e32 v3, v12, v19
	v_min_f32_e32 v12, v12, v19
	v_max_f32_e32 v19, v21, v20
	v_min_f32_e32 v20, v21, v20
	v_max_f32_e32 v21, v26, v11
	v_min_f32_e32 v11, v26, v11
	v_max_f32_e32 v30, v33, v6
	v_min_f32_e32 v6, v33, v6
	v_max_f32_e32 v33, v14, v9
	v_min_f32_e32 v9, v14, v9
	v_max_f32_e32 v14, v31, v16
	v_min_f32_e32 v16, v31, v16
	v_max_f32_e32 v31, v17, v7
	v_min_f32_e32 v7, v17, v7
	v_max_f32_e32 v17, v22, v24
	v_min_f32_e32 v22, v22, v24
	v_max_f32_e32 v24, v32, v23
	v_min_f32_e32 v23, v32, v23
	v_max_f32_e32 v32, v101, v15
	v_min_f32_e32 v15, v101, v15
	v_max_f32_e32 v101, v8, v25
	v_min_f32_e32 v8, v8, v25
	v_max_f32_e32 v26, v29, v2
	v_min_f32_e32 v2, v29, v2
	v_max_f32_e32 v29, v10, v5
	v_min_f32_e32 v5, v10, v5
	v_max_f32_e32 v10, v27, v12
	v_min_f32_e32 v12, v27, v12
	v_max_f32_e32 v27, v13, v3
	v_min_f32_e32 v3, v13, v3
	v_max_f32_e32 v13, v18, v20
	v_min_f32_e32 v18, v18, v20
	v_max_f32_e32 v20, v28, v19
; DEV void ce(float& a, float& b) { float hi = fmaxf(a, b), lo = fminf(a, b); a = hi; b = lo; }
; DEV void sort16_desc(float (&a)[16]) {
; #pragma unroll
;   for (int k = 2; k <= 16; k <<= 1)
; #pragma unroll
;     for (int j = k >> 1; j > 0; j >>= 1)
; #pragma unroll
;       for (int i = 0; i < 16; i++) {
;         const int p = i ^ j;
;         if (p > i) { if ((i & k) == 0) ce(a[i], a[p]); else ce(a[p], a[i]); }
;       }
; }
; DEV void merge_xor(float (&l)[16], int mask) {
;   float t[16];
; #pragma unroll
;   for (int i = 0; i < 16; i++) t[i] = __shfl_xor(l[15 - i], mask);
; #pragma unroll
;   for (int i = 0; i < 16; i++) l[i] = fmaxf(l[i], t[i]);
;   bitonic16(l);
; }
	v_min_f32_e32 v19, v28, v19
	v_max_f32_e32 v28, v109, v11
	v_min_f32_e32 v11, v109, v11
	v_max_f32_e32 v109, v4, v21
	v_min_f32_e32 v4, v4, v21
	v_max_f32_e32 v25, v30, v17
	v_min_f32_e32 v17, v30, v17
	v_max_f32_e32 v30, v33, v24
	v_min_f32_e32 v24, v33, v24
	v_max_f32_e32 v33, v14, v32
	v_min_f32_e32 v14, v14, v32
	v_max_f32_e32 v32, v31, v101
	v_min_f32_e32 v31, v31, v101
	v_max_f32_e32 v101, v6, v22
	v_min_f32_e32 v6, v6, v22
	v_max_f32_e32 v22, v9, v23
	v_min_f32_e32 v9, v9, v23
	v_max_f32_e32 v23, v16, v15
	v_min_f32_e32 v15, v16, v15
	v_max_f32_e32 v16, v7, v8
	v_min_f32_e32 v7, v7, v8
	v_max_f32_e32 v21, v26, v13
	v_min_f32_e32 v13, v26, v13
	v_max_f32_e32 v26, v29, v20
	v_min_f32_e32 v20, v29, v20
	v_max_f32_e32 v29, v10, v28
	v_min_f32_e32 v10, v10, v28
	v_max_f32_e32 v28, v27, v109
	v_min_f32_e32 v27, v27, v109
	v_max_f32_e32 v109, v2, v18
	v_min_f32_e32 v2, v2, v18
	v_max_f32_e32 v18, v5, v19
	v_min_f32_e32 v5, v5, v19
	v_max_f32_e32 v19, v12, v11
	v_min_f32_e32 v11, v12, v11
	v_max_f32_e32 v12, v3, v4
	v_min_f32_e32 v3, v3, v4
	v_max_f32_e32 v111, v0, v43
	v_min_f32_e32 v112, v104, v39
	v_max_f32_e32 v103, v104, v39
	v_min_f32_e32 v0, v0, v43
	v_max_f32_e32 v8, v25, v33
	v_min_f32_e32 v25, v25, v33
	v_max_f32_e32 v33, v30, v32
	v_min_f32_e32 v30, v30, v32
	v_max_f32_e32 v32, v17, v14
	v_min_f32_e32 v14, v17, v14
	v_max_f32_e32 v17, v24, v31
	v_min_f32_e32 v24, v24, v31
	v_max_f32_e32 v31, v101, v23
	v_min_f32_e32 v23, v101, v23
	v_max_f32_e32 v101, v22, v16
	v_min_f32_e32 v16, v22, v16
	v_max_f32_e32 v22, v6, v15
	v_min_f32_e32 v6, v6, v15
	v_max_f32_e32 v15, v9, v7
	v_min_f32_e32 v7, v9, v7
	v_max_f32_e32 v4, v21, v29
	v_min_f32_e32 v21, v21, v29
	v_max_f32_e32 v29, v26, v28
	v_min_f32_e32 v26, v26, v28
	v_max_f32_e32 v28, v13, v10
	v_min_f32_e32 v10, v13, v10
	v_max_f32_e32 v13, v20, v27
	v_min_f32_e32 v20, v20, v27
	v_max_f32_e32 v27, v109, v19
	v_min_f32_e32 v19, v109, v19
	v_max_f32_e32 v109, v18, v12
	v_min_f32_e32 v12, v18, v12
	v_max_f32_e32 v18, v2, v11
	v_min_f32_e32 v2, v2, v11
	v_max_f32_e32 v11, v5, v3
	v_min_f32_e32 v3, v5, v3
	v_min_f32_e32 v63, v107, v108
	v_min_f32_e32 v39, v111, v103
	v_max_f32_e32 v71, v107, v108
	v_max_f32_e32 v51, v111, v103
	v_max_f32_e32 v43, v0, v112
	v_min_f32_e32 v0, v0, v112
	v_min_f32_e32 v9, v8, v33
	v_min_f32_e32 v102, v25, v30
	v_min_f32_e32 v103, v32, v17
	v_min_f32_e32 v104, v14, v24
	v_min_f32_e32 v105, v31, v101
	v_min_f32_e32 v106, v23, v16
	v_min_f32_e32 v107, v22, v15
	v_min_f32_e32 v108, v6, v7
	v_min_f32_e32 v5, v4, v29
	v_min_f32_e32 v110, v21, v26
	v_min_f32_e32 v111, v28, v13
	v_min_f32_e32 v112, v10, v20
	v_min_f32_e32 v113, v27, v109
	v_min_f32_e32 v114, v19, v12
	v_min_f32_e32 v115, v18, v11
	v_min_f32_e32 v116, v2, v3
	v_max3_f32 v8, v8, v33, v116
	v_max3_f32 v2, v9, v2, v3
	v_max3_f32 v3, v25, v30, v115
	v_max3_f32 v9, v102, v18, v11
	v_max3_f32 v11, v32, v17, v114
	v_max3_f32 v12, v103, v19, v12
	v_max3_f32 v14, v14, v24, v113
	v_max3_f32 v17, v104, v27, v109
	v_max3_f32 v18, v31, v101, v112
	v_max3_f32 v10, v105, v10, v20
	v_max3_f32 v16, v23, v16, v111
	v_max3_f32 v13, v106, v28, v13
	v_max3_f32 v15, v22, v15, v110
	v_max3_f32 v19, v107, v21, v26
	v_max3_f32 v5, v6, v7, v5
	v_max3_f32 v4, v108, v4, v29
	v_max_f32_e32 v6, v8, v18
	v_min_f32_e32 v7, v8, v18
	v_max_f32_e32 v8, v2, v10
	v_min_f32_e32 v2, v2, v10
	v_max_f32_e32 v10, v3, v16
	v_min_f32_e32 v3, v3, v16
	v_max_f32_e32 v16, v9, v13
	v_min_f32_e32 v9, v9, v13
	v_max_f32_e32 v13, v11, v15
	v_min_f32_e32 v11, v11, v15
	v_max_f32_e32 v15, v12, v19
	v_min_f32_e32 v12, v12, v19
	v_max_f32_e32 v18, v14, v5
	v_min_f32_e32 v5, v14, v5
	v_max_f32_e32 v14, v17, v4
	v_min_f32_e32 v4, v17, v4
	v_max_f32_e32 v17, v6, v13
	v_min_f32_e32 v6, v6, v13
	v_max_f32_e32 v13, v8, v15
	v_min_f32_e32 v8, v8, v15
	v_max_f32_e32 v15, v10, v18
	v_min_f32_e32 v10, v10, v18
	v_max_f32_e32 v18, v16, v14
	v_min_f32_e32 v14, v16, v14
	v_max_f32_e32 v16, v7, v11
	v_min_f32_e32 v7, v7, v11
	v_max_f32_e32 v11, v2, v12
	v_min_f32_e32 v2, v2, v12
	v_max_f32_e32 v12, v3, v5
	v_min_f32_e32 v3, v3, v5
	v_max_f32_e32 v5, v9, v4
	v_min_f32_e32 v4, v9, v4
	v_max_f32_e32 v9, v17, v15
	v_min_f32_e32 v15, v17, v15
	v_max_f32_e32 v17, v13, v18
	v_min_f32_e32 v13, v13, v18
	v_max_f32_e32 v18, v6, v10
	v_min_f32_e32 v6, v6, v10
	v_max_f32_e32 v10, v8, v14
	v_min_f32_e32 v8, v8, v14
	v_max_f32_e32 v14, v16, v12
	v_min_f32_e32 v12, v16, v12
	v_max_f32_e32 v16, v11, v5
	v_min_f32_e32 v5, v11, v5
	v_max_f32_e32 v11, v7, v3
	v_min_f32_e32 v3, v7, v3
	v_max_f32_e32 v7, v2, v4
	v_min_f32_e32 v2, v2, v4
	v_max_f32_e32 v4, v9, v17
	v_min_f32_e32 v9, v9, v17
	v_max_f32_e32 v17, v15, v13
	v_min_f32_e32 v13, v15, v13
	v_max_f32_e32 v15, v18, v10
	v_min_f32_e32 v10, v18, v10
	v_max_f32_e32 v18, v6, v8
	v_min_f32_e32 v6, v6, v8
	v_max_f32_e32 v8, v14, v16
	v_min_f32_e32 v14, v14, v16
	v_max_f32_e32 v16, v12, v5
	v_min_f32_e32 v5, v12, v5
	v_max_f32_e32 v12, v11, v7
	v_min_f32_e32 v7, v11, v7
	v_max_f32_e32 v11, v3, v2
	v_min_f32_e32 v2, v3, v2
	ds_bpermute_b32 v3, v95, v2
	ds_bpermute_b32 v19, v95, v11
	ds_bpermute_b32 v20, v95, v7
	ds_bpermute_b32 v21, v95, v12
	ds_bpermute_b32 v22, v95, v5
	ds_bpermute_b32 v23, v95, v16
	s_waitcnt lgkmcnt(5)
	ds_bpermute_b32 v24, v95, v14
	ds_bpermute_b32 v33, v95, v4
	v_max_f32_e32 v3, v4, v3
	s_waitcnt lgkmcnt(6)
	ds_bpermute_b32 v25, v95, v8
	ds_bpermute_b32 v32, v95, v9
	v_max_f32_e32 v4, v9, v19
	s_waitcnt lgkmcnt(7)
	ds_bpermute_b32 v26, v95, v6
	ds_bpermute_b32 v31, v95, v17
	v_max_f32_e32 v9, v17, v20
	s_waitcnt lgkmcnt(8)
	ds_bpermute_b32 v27, v95, v18
	ds_bpermute_b32 v30, v95, v13
	v_max_f32_e32 v13, v13, v21
	s_waitcnt lgkmcnt(9)
; DEV void merge_xor(float (&l)[16], int mask) {
;   float t[16];
; #pragma unroll
;   for (int i = 0; i < 16; i++) t[i] = __shfl_xor(l[15 - i], mask);
; #pragma unroll
;   for (int i = 0; i < 16; i++) l[i] = fmaxf(l[i], t[i]);
;   bitonic16(l);
; }
; DEV void phase_peer_score(const Params& p, int layer, int M, char* smem) {
;     ...
;     unsigned char* tab = (unsigned char*)smem + 73728 + (w * 16 + l15) * 32;
; #pragma unroll
;     for (int i = 0; i < 16; i++) { tab[i] = (unsigned char)(__float_as_uint(L0[i]) & 127u); tab[16 + i] = (unsigned char)(__float_as_uint(L1[i]) & 127u); }
	ds_bpermute_b32 v28, v95, v10
	ds_bpermute_b32 v29, v95, v15
	v_max_f32_e32 v15, v15, v22
	s_waitcnt lgkmcnt(10)
	v_max_f32_e32 v10, v10, v23
	s_waitcnt lgkmcnt(9)
	v_max_f32_e32 v17, v18, v24
	s_waitcnt lgkmcnt(7)
	v_max_f32_e32 v6, v6, v25
	s_waitcnt lgkmcnt(5)
	v_max_f32_e32 v8, v8, v26
	s_waitcnt lgkmcnt(3)
	v_max_f32_e32 v14, v14, v27
	s_waitcnt lgkmcnt(1)
	v_max_f32_e32 v16, v16, v28
	s_waitcnt lgkmcnt(0)
	v_max_f32_e32 v5, v5, v29
	v_max_f32_e32 v12, v12, v30
	v_max_f32_e32 v7, v7, v31
	v_max_f32_e32 v11, v11, v32
	v_max_f32_e32 v2, v2, v33
	v_max_f32_e32 v18, v3, v8
	v_min_f32_e32 v3, v3, v8
	v_max_f32_e32 v8, v4, v14
	v_min_f32_e32 v4, v4, v14
	v_max_f32_e32 v14, v9, v16
	v_min_f32_e32 v9, v9, v16
	v_max_f32_e32 v16, v13, v5
	v_min_f32_e32 v5, v13, v5
	v_max_f32_e32 v13, v15, v12
	v_min_f32_e32 v12, v15, v12
	v_max_f32_e32 v15, v10, v7
	v_min_f32_e32 v7, v10, v7
	v_max_f32_e32 v10, v17, v11
	v_min_f32_e32 v11, v17, v11
	v_max_f32_e32 v17, v6, v2
	v_min_f32_e32 v2, v6, v2
	v_max_f32_e32 v6, v18, v13
	v_min_f32_e32 v13, v18, v13
	v_max_f32_e32 v18, v8, v15
	v_min_f32_e32 v8, v8, v15
	v_max_f32_e32 v15, v14, v10
	v_min_f32_e32 v10, v14, v10
	v_max_f32_e32 v14, v16, v17
	v_min_f32_e32 v16, v16, v17
	v_max_f32_e32 v17, v3, v12
	v_min_f32_e32 v3, v3, v12
	v_max_f32_e32 v12, v4, v7
	v_min_f32_e32 v4, v4, v7
	v_max_f32_e32 v7, v9, v11
	v_min_f32_e32 v9, v9, v11
	v_max_f32_e32 v11, v5, v2
	v_min_f32_e32 v2, v5, v2
	v_max_f32_e32 v5, v6, v15
	v_min_f32_e32 v6, v6, v15
	v_max_f32_e32 v15, v18, v14
	v_min_f32_e32 v14, v18, v14
	v_max_f32_e32 v18, v13, v10
	v_min_f32_e32 v10, v13, v10
	v_max_f32_e32 v13, v8, v16
	v_min_f32_e32 v8, v8, v16
	v_max_f32_e32 v16, v17, v7
	v_min_f32_e32 v7, v17, v7
	v_max_f32_e32 v17, v12, v11
	v_min_f32_e32 v11, v12, v11
	v_max_f32_e32 v12, v3, v9
	v_min_f32_e32 v3, v3, v9
	v_max_f32_e32 v9, v4, v2
	v_min_f32_e32 v2, v4, v2
	v_max_f32_e32 v4, v5, v15
	v_min_f32_e32 v5, v5, v15
	v_max_f32_e32 v15, v6, v14
	v_min_f32_e32 v6, v6, v14
	v_max_f32_e32 v14, v18, v13
	v_min_f32_e32 v13, v18, v13
	v_max_f32_e32 v18, v10, v8
	v_min_f32_e32 v8, v10, v8
	v_max_f32_e32 v10, v16, v17
	v_min_f32_e32 v16, v16, v17
	v_max_f32_e32 v17, v7, v11
	v_min_f32_e32 v7, v7, v11
	v_max_f32_e32 v11, v12, v9
	v_min_f32_e32 v9, v12, v9
	v_max_f32_e32 v12, v3, v2
	v_min_f32_e32 v2, v3, v2
	ds_bpermute_b32 v3, v99, v2
	ds_bpermute_b32 v19, v99, v12
	ds_bpermute_b32 v20, v99, v9
	ds_bpermute_b32 v21, v99, v11
	ds_bpermute_b32 v22, v99, v7
	ds_bpermute_b32 v23, v99, v17
	s_waitcnt lgkmcnt(5)
	ds_bpermute_b32 v24, v99, v16
	ds_bpermute_b32 v33, v99, v4
	v_max_f32_e32 v3, v4, v3
	s_waitcnt lgkmcnt(6)
	ds_bpermute_b32 v25, v99, v10
	ds_bpermute_b32 v32, v99, v5
	v_max_f32_e32 v4, v5, v19
	s_waitcnt lgkmcnt(7)
	ds_bpermute_b32 v26, v99, v8
	ds_bpermute_b32 v31, v99, v15
	v_max_f32_e32 v5, v15, v20
	s_waitcnt lgkmcnt(8)
	ds_bpermute_b32 v27, v99, v18
	ds_bpermute_b32 v30, v99, v6
	v_max_f32_e32 v6, v6, v21
	s_waitcnt lgkmcnt(9)
	ds_bpermute_b32 v28, v99, v13
	ds_bpermute_b32 v29, v99, v14
	v_max_f32_e32 v14, v14, v22
	s_waitcnt lgkmcnt(10)
	v_max_f32_e32 v13, v13, v23
	s_waitcnt lgkmcnt(9)
	v_max_f32_e32 v15, v18, v24
	s_waitcnt lgkmcnt(7)
	v_max_f32_e32 v8, v8, v25
	s_waitcnt lgkmcnt(5)
	v_max_f32_e32 v10, v10, v26
	s_waitcnt lgkmcnt(3)
	v_max_f32_e32 v16, v16, v27
	s_waitcnt lgkmcnt(1)
	v_max_f32_e32 v17, v17, v28
	s_waitcnt lgkmcnt(0)
	v_max_f32_e32 v7, v7, v29
	v_max_f32_e32 v11, v11, v30
	v_max_f32_e32 v9, v9, v31
	v_max_f32_e32 v12, v12, v32
	v_max_f32_e32 v2, v2, v33
	v_max_f32_e32 v18, v3, v10
	v_min_f32_e32 v3, v3, v10
	v_max_f32_e32 v10, v4, v16
	v_min_f32_e32 v4, v4, v16
	v_max_f32_e32 v16, v5, v17
	v_min_f32_e32 v5, v5, v17
	v_max_f32_e32 v17, v6, v7
	v_min_f32_e32 v6, v6, v7
	v_max_f32_e32 v7, v14, v11
	v_min_f32_e32 v11, v14, v11
	v_max_f32_e32 v14, v13, v9
	v_min_f32_e32 v9, v13, v9
	v_max_f32_e32 v13, v15, v12
	v_min_f32_e32 v12, v15, v12
	v_max_f32_e32 v15, v8, v2
	v_min_f32_e32 v2, v8, v2
	v_max_f32_e32 v8, v18, v7
	v_min_f32_e32 v7, v18, v7
	v_max_f32_e32 v18, v10, v14
	v_min_f32_e32 v10, v10, v14
	v_max_f32_e32 v14, v16, v13
	v_min_f32_e32 v13, v16, v13
	v_max_f32_e32 v16, v17, v15
	v_min_f32_e32 v15, v17, v15
	v_max_f32_e32 v17, v3, v11
	v_min_f32_e32 v3, v3, v11
	v_max_f32_e32 v11, v4, v9
	v_min_f32_e32 v4, v4, v9
	v_max_f32_e32 v9, v5, v12
	v_min_f32_e32 v5, v5, v12
	v_max_f32_e32 v12, v6, v2
	v_min_f32_e32 v2, v6, v2
	v_max_f32_e32 v6, v8, v14
	v_min_f32_e32 v8, v8, v14
	v_max_f32_e32 v14, v18, v16
	v_min_f32_e32 v16, v18, v16
	v_max_f32_e32 v18, v7, v13
	v_max_f32_e32 v19, v10, v15
	s_movk_i32 s8, 0x7f
	v_min_f32_e32 v13, v7, v13
	v_min_f32_e32 v10, v10, v15
	v_max_f32_e32 v15, v17, v9
	v_min_f32_e32 v21, v17, v9
	v_max_f32_e32 v17, v11, v12
	v_min_f32_e32 v22, v11, v12
	v_max_f32_e32 v23, v3, v5
	v_min_f32_e32 v3, v3, v5
	v_max_f32_e32 v5, v4, v2
	v_min_f32_e32 v24, v4, v2
	v_max_f32_e32 v9, v18, v19
	v_min_f32_e32 v12, v18, v19
	v_and_b32_sdwa v18, v63, s8 dst_sel:BYTE_1 dst_unused:UNUSED_PAD src0_sel:DWORD src1_sel:DWORD
	v_max_f32_e32 v2, v6, v14
	v_min_f32_e32 v4, v6, v14
	v_max_f32_e32 v11, v13, v10
	v_min_f32_e32 v10, v13, v10
	v_max_f32_e32 v14, v23, v5
	v_min_f32_e32 v13, v23, v5
	v_max_f32_e32 v6, v3, v24
	v_min_f32_e32 v5, v3, v24
	v_and_b32_sdwa v3, v75, s8 dst_sel:BYTE_1 dst_unused:UNUSED_PAD src0_sel:DWORD src1_sel:DWORD
	v_bitop3_b16 v18, v71, v18, s8 bitop3:0xec
	v_bitop3_b16 v3, v79, v3, s8 bitop3:0xec
	v_lshlrev_b32_e32 v18, 16, v18
	v_or_b32_sdwa v23, v3, v18 dst_sel:DWORD dst_unused:UNUSED_PAD src0_sel:WORD_0 src1_sel:DWORD
	v_and_b32_sdwa v18, v83, s8 dst_sel:BYTE_1 dst_unused:UNUSED_PAD src0_sel:DWORD src1_sel:DWORD
; DEV void ce(float& a, float& b) { float hi = fmaxf(a, b), lo = fminf(a, b); a = hi; b = lo; }
; DEV void phase_peer_score(const Params& p, int layer, int M, char* smem) {
;     ...
;     float R[16];
; #pragma unroll
;     for (int i = 0; i < 16; i++) R[i] = -3.0e38f;
; #pragma unroll
;     for (int i = 0; i < 16; i++)
; #pragma unroll
;       for (int j = 0; j < 16; j++)
;         if ((i + 1) * (j + 1) <= 16) {
;           float v = L0[i] + L1[j];
;           v = __uint_as_float((__float_as_uint(v) & ~255u) | (unsigned)(i * 16 + j));
; #pragma unroll
;           for (int t = 0; t < 16; t++)
;             if (t >= (i + 1) * (j + 1) - 1) ce(R[t], v);
;         }
;     unsigned char* tab = (unsigned char*)smem + 73728 + (w * 16 + l15) * 32;
; #pragma unroll
;     for (int i = 0; i < 16; i++) { tab[i] = (unsigned char)(__float_as_uint(L0[i]) & 127u); tab[16 + i] = (unsigned char)(__float_as_uint(L1[i]) & 127u); }
	v_and_b32_sdwa v3, v91, s8 dst_sel:BYTE_1 dst_unused:UNUSED_PAD src0_sel:DWORD src1_sel:DWORD
	v_bitop3_b16 v18, v87, v18, s8 bitop3:0xec
	v_bitop3_b16 v3, v100, v3, s8 bitop3:0xec
	v_lshlrev_b32_e32 v18, 16, v18
	v_max_f32_e32 v7, v8, v16
	v_min_f32_e32 v8, v8, v16
	v_max_f32_e32 v20, v15, v17
	v_min_f32_e32 v17, v15, v17
	v_max_f32_e32 v16, v21, v22
	v_min_f32_e32 v15, v21, v22
	v_or_b32_sdwa v22, v3, v18 dst_sel:DWORD dst_unused:UNUSED_PAD src0_sel:WORD_0 src1_sel:DWORD
	v_and_b32_sdwa v18, v10, s8 dst_sel:BYTE_1 dst_unused:UNUSED_PAD src0_sel:DWORD src1_sel:DWORD
	v_and_b32_sdwa v3, v12, s8 dst_sel:BYTE_1 dst_unused:UNUSED_PAD src0_sel:DWORD src1_sel:DWORD
	v_bitop3_b16 v18, v11, v18, s8 bitop3:0xec
	v_bitop3_b16 v3, v9, v3, s8 bitop3:0xec
	v_lshlrev_b32_e32 v18, 16, v18
	v_or_b32_sdwa v27, v3, v18 dst_sel:DWORD dst_unused:UNUSED_PAD src0_sel:WORD_0 src1_sel:DWORD
	v_and_b32_sdwa v18, v8, s8 dst_sel:BYTE_1 dst_unused:UNUSED_PAD src0_sel:DWORD src1_sel:DWORD
	v_and_b32_sdwa v3, v4, s8 dst_sel:BYTE_1 dst_unused:UNUSED_PAD src0_sel:DWORD src1_sel:DWORD
	v_bitop3_b16 v18, v7, v18, s8 bitop3:0xec
	v_bitop3_b16 v3, v2, v3, s8 bitop3:0xec
	v_lshlrev_b32_e32 v18, 16, v18
	v_or_b32_sdwa v26, v3, v18 dst_sel:DWORD dst_unused:UNUSED_PAD src0_sel:WORD_0 src1_sel:DWORD
	v_and_b32_sdwa v18, v0, s8 dst_sel:BYTE_1 dst_unused:UNUSED_PAD src0_sel:DWORD src1_sel:DWORD
	v_and_b32_sdwa v3, v39, s8 dst_sel:BYTE_1 dst_unused:UNUSED_PAD src0_sel:DWORD src1_sel:DWORD
	v_bitop3_b16 v18, v43, v18, s8 bitop3:0xec
	v_bitop3_b16 v3, v51, v3, s8 bitop3:0xec
	v_lshlrev_b32_e32 v18, 16, v18
	v_or_b32_sdwa v25, v3, v18 dst_sel:DWORD dst_unused:UNUSED_PAD src0_sel:WORD_0 src1_sel:DWORD
	v_and_b32_sdwa v18, v47, s8 dst_sel:BYTE_1 dst_unused:UNUSED_PAD src0_sel:DWORD src1_sel:DWORD
	v_and_b32_sdwa v3, v59, s8 dst_sel:BYTE_1 dst_unused:UNUSED_PAD src0_sel:DWORD src1_sel:DWORD
	v_bitop3_b16 v18, v55, v18, s8 bitop3:0xec
	v_bitop3_b16 v3, v67, v3, s8 bitop3:0xec
	v_lshlrev_b32_e32 v18, 16, v18
	v_or_b32_sdwa v24, v3, v18 dst_sel:DWORD dst_unused:UNUSED_PAD src0_sel:WORD_0 src1_sel:DWORD
	v_and_b32_sdwa v18, v5, s8 dst_sel:BYTE_1 dst_unused:UNUSED_PAD src0_sel:DWORD src1_sel:DWORD
	v_and_b32_sdwa v3, v13, s8 dst_sel:BYTE_1 dst_unused:UNUSED_PAD src0_sel:DWORD src1_sel:DWORD
	v_bitop3_b16 v18, v6, v18, s8 bitop3:0xec
	v_bitop3_b16 v3, v14, v3, s8 bitop3:0xec
	v_lshlrev_b32_e32 v18, 16, v18
	v_or_b32_sdwa v29, v3, v18 dst_sel:DWORD dst_unused:UNUSED_PAD src0_sel:WORD_0 src1_sel:DWORD
	v_and_b32_sdwa v18, v15, s8 dst_sel:BYTE_1 dst_unused:UNUSED_PAD src0_sel:DWORD src1_sel:DWORD
	v_and_b32_sdwa v3, v17, s8 dst_sel:BYTE_1 dst_unused:UNUSED_PAD src0_sel:DWORD src1_sel:DWORD
	v_bitop3_b16 v18, v16, v18, s8 bitop3:0xec
	v_bitop3_b16 v3, v20, v3, s8 bitop3:0xec
	v_lshlrev_b32_e32 v18, 16, v18
	v_or_b32_sdwa v28, v3, v18 dst_sel:DWORD dst_unused:UNUSED_PAD src0_sel:WORD_0 src1_sel:DWORD
	ds_write_b128 v138, v[22:25]
	ds_write_b128 v138, v[26:29] offset:16
	s_and_saveexec_b64 s[8:9], s[38:39]
	s_cbranch_execz .LBB0_627
	s_movk_i32 s18, 0xff00
	v_add_f32_e32 v164, v100, v2
	v_and_or_b32 v164, v164, s18, 0
	v_max_f32_e32 v148, 0xff61b1e6, v164
	v_add_f32_e32 v164, v100, v4
	v_and_or_b32 v164, v164, s18, 1
	v_max_f32_e32 v149, 0xff61b1e6, v164
	v_add_f32_e32 v164, v100, v7
	v_and_or_b32 v164, v164, s18, 2
	v_max_f32_e32 v150, 0xff61b1e6, v164
	v_add_f32_e32 v164, v100, v8
	v_and_or_b32 v164, v164, s18, 3
	v_max_f32_e32 v151, 0xff61b1e6, v164
	v_add_f32_e32 v164, v100, v9
	v_and_or_b32 v164, v164, s18, 4
	v_max_f32_e32 v152, 0xff61b1e6, v164
	v_add_f32_e32 v164, v100, v12
	v_and_or_b32 v164, v164, s18, 5
	v_max_f32_e32 v153, 0xff61b1e6, v164
	v_add_f32_e32 v164, v100, v11
	v_and_or_b32 v164, v164, s18, 6
	v_max_f32_e32 v154, 0xff61b1e6, v164
	v_add_f32_e32 v164, v100, v10
	v_and_or_b32 v164, v164, s18, 7
	v_max_f32_e32 v155, 0xff61b1e6, v164
	v_add_f32_e32 v164, v100, v20
	v_and_or_b32 v164, v164, s18, 8
	v_max_f32_e32 v156, 0xff61b1e6, v164
	v_add_f32_e32 v164, v100, v17
	v_and_or_b32 v164, v164, s18, 9
	v_max_f32_e32 v157, 0xff61b1e6, v164
	v_add_f32_e32 v164, v100, v16
	v_and_or_b32 v164, v164, s18, 10
	v_max_f32_e32 v158, 0xff61b1e6, v164
	v_add_f32_e32 v164, v100, v15
	v_and_or_b32 v164, v164, s18, 11
	v_max_f32_e32 v159, 0xff61b1e6, v164
	v_add_f32_e32 v164, v100, v14
	v_and_or_b32 v164, v164, s18, 12
	v_max_f32_e32 v160, 0xff61b1e6, v164
	v_add_f32_e32 v164, v100, v13
	v_and_or_b32 v164, v164, s18, 13
	v_max_f32_e32 v161, 0xff61b1e6, v164
	v_add_f32_e32 v164, v100, v6
	v_and_or_b32 v164, v164, s18, 14
	v_max_f32_e32 v162, 0xff61b1e6, v164
	v_add_f32_e32 v164, v100, v5
	v_and_or_b32 v164, v164, s18, 15
	v_max_f32_e32 v163, 0xff61b1e6, v164
	v_add_f32_e32 v164, v91, v2
	v_and_or_b32 v164, v164, s18, 16
	v_med3_f32 v163, v162, v163, v164
	v_med3_f32 v162, v161, v162, v164
	v_med3_f32 v161, v160, v161, v164
	v_med3_f32 v160, v159, v160, v164
	v_med3_f32 v159, v158, v159, v164
	v_med3_f32 v158, v157, v158, v164
	v_med3_f32 v157, v156, v157, v164
	v_med3_f32 v156, v155, v156, v164
	v_med3_f32 v155, v154, v155, v164
	v_med3_f32 v154, v153, v154, v164
	v_med3_f32 v153, v152, v153, v164
	v_med3_f32 v152, v151, v152, v164
	v_med3_f32 v151, v150, v151, v164
	v_med3_f32 v150, v149, v150, v164
	v_max_f32_e32 v149, v149, v164
	v_add_f32_e32 v164, v91, v4
	v_and_or_b32 v164, v164, s18, 17
	v_med3_f32 v163, v162, v163, v164
	v_med3_f32 v162, v161, v162, v164
	v_med3_f32 v161, v160, v161, v164
	v_med3_f32 v160, v159, v160, v164
	v_med3_f32 v159, v158, v159, v164
	v_med3_f32 v158, v157, v158, v164
	v_med3_f32 v157, v156, v157, v164
	v_med3_f32 v156, v155, v156, v164
	v_med3_f32 v155, v154, v155, v164
; DEV void ce(float& a, float& b) { float hi = fmaxf(a, b), lo = fminf(a, b); a = hi; b = lo; }
; DEV void phase_peer_score(const Params& p, int layer, int M, char* smem) {
;     ...
;     float R[16];
; #pragma unroll
;     for (int i = 0; i < 16; i++) R[i] = -3.0e38f;
; #pragma unroll
;     for (int i = 0; i < 16; i++)
; #pragma unroll
;       for (int j = 0; j < 16; j++)
;         if ((i + 1) * (j + 1) <= 16) {
;           float v = L0[i] + L1[j];
;           v = __uint_as_float((__float_as_uint(v) & ~255u) | (unsigned)(i * 16 + j));
; #pragma unroll
;           for (int t = 0; t < 16; t++)
;             if (t >= (i + 1) * (j + 1) - 1) ce(R[t], v);
;         }
	v_med3_f32 v154, v153, v154, v164
	v_med3_f32 v153, v152, v153, v164
	v_med3_f32 v152, v151, v152, v164
	v_max_f32_e32 v151, v151, v164
	v_add_f32_e32 v164, v91, v7
	v_and_or_b32 v164, v164, s18, 18
	v_med3_f32 v163, v162, v163, v164
	v_med3_f32 v162, v161, v162, v164
	v_med3_f32 v161, v160, v161, v164
	v_med3_f32 v160, v159, v160, v164
	v_med3_f32 v159, v158, v159, v164
	v_med3_f32 v158, v157, v158, v164
	v_med3_f32 v157, v156, v157, v164
	v_med3_f32 v156, v155, v156, v164
	v_med3_f32 v155, v154, v155, v164
	v_med3_f32 v154, v153, v154, v164
	v_max_f32_e32 v153, v153, v164
	v_add_f32_e32 v164, v91, v8
	v_and_or_b32 v164, v164, s18, 19
	v_med3_f32 v163, v162, v163, v164
	v_med3_f32 v162, v161, v162, v164
	v_med3_f32 v161, v160, v161, v164
	v_med3_f32 v160, v159, v160, v164
	v_med3_f32 v159, v158, v159, v164
	v_med3_f32 v158, v157, v158, v164
	v_med3_f32 v157, v156, v157, v164
	v_med3_f32 v156, v155, v156, v164
	v_max_f32_e32 v155, v155, v164
	v_add_f32_e32 v164, v91, v9
	v_and_or_b32 v164, v164, s18, 20
	v_med3_f32 v163, v162, v163, v164
	v_med3_f32 v162, v161, v162, v164
	v_med3_f32 v161, v160, v161, v164
	v_med3_f32 v160, v159, v160, v164
	v_med3_f32 v159, v158, v159, v164
	v_med3_f32 v158, v157, v158, v164
	v_max_f32_e32 v157, v157, v164
	v_add_f32_e32 v164, v91, v12
	v_and_or_b32 v164, v164, s18, 21
	v_med3_f32 v163, v162, v163, v164
	v_med3_f32 v162, v161, v162, v164
	v_med3_f32 v161, v160, v161, v164
	v_med3_f32 v160, v159, v160, v164
	v_max_f32_e32 v159, v159, v164
	v_add_f32_e32 v164, v91, v11
	v_and_or_b32 v164, v164, s18, 22
	v_med3_f32 v163, v162, v163, v164
	v_med3_f32 v162, v161, v162, v164
	v_max_f32_e32 v161, v161, v164
	v_add_f32_e32 v164, v91, v10
	v_and_or_b32 v164, v164, s18, 23
	v_max_f32_e32 v163, v163, v164
	v_add_f32_e32 v164, v87, v2
	v_and_or_b32 v164, v164, s18, 32
	v_med3_f32 v163, v162, v163, v164
	v_med3_f32 v162, v161, v162, v164
	v_med3_f32 v161, v160, v161, v164
	v_med3_f32 v160, v159, v160, v164
	v_med3_f32 v159, v158, v159, v164
	v_med3_f32 v158, v157, v158, v164
	v_med3_f32 v157, v156, v157, v164
	v_med3_f32 v156, v155, v156, v164
	v_med3_f32 v155, v154, v155, v164
	v_med3_f32 v154, v153, v154, v164
	v_med3_f32 v153, v152, v153, v164
	v_med3_f32 v152, v151, v152, v164
	v_med3_f32 v151, v150, v151, v164
	v_max_f32_e32 v150, v150, v164
	v_add_f32_e32 v164, v87, v4
	v_and_or_b32 v164, v164, s18, 33
	v_med3_f32 v163, v162, v163, v164
	v_med3_f32 v162, v161, v162, v164
	v_med3_f32 v161, v160, v161, v164
	v_med3_f32 v160, v159, v160, v164
	v_med3_f32 v159, v158, v159, v164
	v_med3_f32 v158, v157, v158, v164
	v_med3_f32 v157, v156, v157, v164
	v_med3_f32 v156, v155, v156, v164
	v_med3_f32 v155, v154, v155, v164
	v_med3_f32 v154, v153, v154, v164
	v_max_f32_e32 v153, v153, v164
	v_add_f32_e32 v164, v87, v7
	v_and_or_b32 v164, v164, s18, 34
	v_med3_f32 v163, v162, v163, v164
	v_med3_f32 v162, v161, v162, v164
	v_med3_f32 v161, v160, v161, v164
	v_med3_f32 v160, v159, v160, v164
	v_med3_f32 v159, v158, v159, v164
	v_med3_f32 v158, v157, v158, v164
	v_med3_f32 v157, v156, v157, v164
	v_max_f32_e32 v156, v156, v164
	v_add_f32_e32 v164, v87, v8
	v_and_or_b32 v164, v164, s18, 35
	v_med3_f32 v163, v162, v163, v164
	v_med3_f32 v162, v161, v162, v164
	v_med3_f32 v161, v160, v161, v164
	v_med3_f32 v160, v159, v160, v164
	v_max_f32_e32 v159, v159, v164
	v_add_f32_e32 v164, v87, v9
	v_and_or_b32 v164, v164, s18, 36
	v_med3_f32 v163, v162, v163, v164
	v_max_f32_e32 v162, v162, v164
	v_add_f32_e32 v164, v83, v2
	v_and_or_b32 v164, v164, s18, 48
	v_med3_f32 v163, v162, v163, v164
	v_med3_f32 v162, v161, v162, v164
	v_med3_f32 v161, v160, v161, v164
	v_med3_f32 v160, v159, v160, v164
	v_med3_f32 v159, v158, v159, v164
	v_med3_f32 v158, v157, v158, v164
	v_med3_f32 v157, v156, v157, v164
	v_med3_f32 v156, v155, v156, v164
	v_med3_f32 v155, v154, v155, v164
	v_med3_f32 v154, v153, v154, v164
	v_med3_f32 v153, v152, v153, v164
	v_med3_f32 v152, v151, v152, v164
	v_max_f32_e32 v151, v151, v164
	v_add_f32_e32 v164, v83, v4
	v_and_or_b32 v164, v164, s18, 49
	v_med3_f32 v163, v162, v163, v164
	v_med3_f32 v162, v161, v162, v164
	v_med3_f32 v161, v160, v161, v164
	v_med3_f32 v160, v159, v160, v164
	v_med3_f32 v159, v158, v159, v164
	v_med3_f32 v158, v157, v158, v164
	v_med3_f32 v157, v156, v157, v164
	v_med3_f32 v156, v155, v156, v164
	v_max_f32_e32 v155, v155, v164
	v_add_f32_e32 v164, v83, v7
	v_and_or_b32 v164, v164, s18, 50
	v_med3_f32 v163, v162, v163, v164
	v_med3_f32 v162, v161, v162, v164
	v_med3_f32 v161, v160, v161, v164
	v_med3_f32 v160, v159, v160, v164
	v_max_f32_e32 v159, v159, v164
	v_add_f32_e32 v164, v83, v8
	v_and_or_b32 v164, v164, s18, 51
	v_max_f32_e32 v163, v163, v164
	v_add_f32_e32 v164, v79, v2
	v_and_or_b32 v164, v164, s18, 64
	v_med3_f32 v163, v162, v163, v164
	v_med3_f32 v162, v161, v162, v164
	v_med3_f32 v161, v160, v161, v164
	v_med3_f32 v160, v159, v160, v164
	v_med3_f32 v159, v158, v159, v164
	v_med3_f32 v158, v157, v158, v164
	v_med3_f32 v157, v156, v157, v164
	v_med3_f32 v156, v155, v156, v164
	v_med3_f32 v155, v154, v155, v164
	v_med3_f32 v154, v153, v154, v164
	v_med3_f32 v153, v152, v153, v164
	v_max_f32_e32 v152, v152, v164
	v_add_f32_e32 v164, v79, v4
	v_and_b32_e32 v164, 0xffffff00, v164
	v_or_b32_e32 v164, 0x41, v164
	v_med3_f32 v163, v162, v163, v164
	v_med3_f32 v162, v161, v162, v164
	v_med3_f32 v161, v160, v161, v164
	v_med3_f32 v160, v159, v160, v164
	v_med3_f32 v159, v158, v159, v164
	v_med3_f32 v158, v157, v158, v164
	v_max_f32_e32 v157, v157, v164
	v_add_f32_e32 v164, v79, v7
	v_and_b32_e32 v164, 0xffffff00, v164
	v_or_b32_e32 v164, 0x42, v164
	v_med3_f32 v163, v162, v163, v164
; DEV void ce(float& a, float& b) { float hi = fmaxf(a, b), lo = fminf(a, b); a = hi; b = lo; }
; DEV void phase_peer_score(const Params& p, int layer, int M, char* smem) {
;     ...
;     float R[16];
; #pragma unroll
;     for (int i = 0; i < 16; i++) R[i] = -3.0e38f;
; #pragma unroll
;     for (int i = 0; i < 16; i++)
; #pragma unroll
;       for (int j = 0; j < 16; j++)
;         if ((i + 1) * (j + 1) <= 16) {
;           float v = L0[i] + L1[j];
;           v = __uint_as_float((__float_as_uint(v) & ~255u) | (unsigned)(i * 16 + j));
; #pragma unroll
;           for (int t = 0; t < 16; t++)
;             if (t >= (i + 1) * (j + 1) - 1) ce(R[t], v);
;         }
;     unsigned char* tab = (unsigned char*)smem + 73728 + (w * 16 + l15) * 32;
; #pragma unroll
;     for (int i = 0; i < 16; i++) { tab[i] = (unsigned char)(__float_as_uint(L0[i]) & 127u); tab[16 + i] = (unsigned char)(__float_as_uint(L1[i]) & 127u); }
;     float ev[16]; float sum = 0.f;
; #pragma unroll
;     for (int t = 0; t < 16; t++) { ev[t] = __expf(R[t] - R[0]); sum += ev[t]; }
;     const float inv = 1.f / sum;
;     int eid[16];
; #pragma unroll
;     for (int t = 0; t < 16; t++) {
;       unsigned code = __float_as_uint(R[t]) & 255u;
;       eid[t] = (int)tab[code >> 4] * 128 + (int)tab[16 + (code & 15u)];
	v_max_f32_e32 v162, v162, v164
	v_add_f32_e32 v164, v75, v2
	v_and_b32_e32 v164, 0xffffff00, v164
	v_or_b32_e32 v164, 0x50, v164
	v_med3_f32 v163, v162, v163, v164
	v_med3_f32 v162, v161, v162, v164
	v_med3_f32 v161, v160, v161, v164
	v_med3_f32 v160, v159, v160, v164
	v_med3_f32 v159, v158, v159, v164
	v_med3_f32 v158, v157, v158, v164
	v_med3_f32 v157, v156, v157, v164
	v_med3_f32 v156, v155, v156, v164
	v_med3_f32 v155, v154, v155, v164
	v_med3_f32 v154, v153, v154, v164
	v_max_f32_e32 v153, v153, v164
	v_add_f32_e32 v164, v75, v4
	v_and_b32_e32 v164, 0xffffff00, v164
	v_or_b32_e32 v164, 0x51, v164
	v_med3_f32 v163, v162, v163, v164
	v_med3_f32 v162, v161, v162, v164
	v_med3_f32 v161, v160, v161, v164
	v_med3_f32 v160, v159, v160, v164
	v_max_f32_e32 v159, v159, v164
	v_add_f32_e32 v164, v71, v2
	v_and_b32_e32 v164, 0xffffff00, v164
	v_or_b32_e32 v164, 0x60, v164
	v_med3_f32 v163, v162, v163, v164
	v_med3_f32 v162, v161, v162, v164
	v_med3_f32 v161, v160, v161, v164
	v_med3_f32 v160, v159, v160, v164
	v_med3_f32 v159, v158, v159, v164
	v_med3_f32 v158, v157, v158, v164
	v_med3_f32 v157, v156, v157, v164
	v_med3_f32 v156, v155, v156, v164
	v_med3_f32 v155, v154, v155, v164
	v_max_f32_e32 v154, v154, v164
	v_add_f32_e32 v164, v71, v4
	v_and_b32_e32 v164, 0xffffff00, v164
	v_or_b32_e32 v164, 0x61, v164
	v_med3_f32 v163, v162, v163, v164
	v_med3_f32 v162, v161, v162, v164
	v_max_f32_e32 v161, v161, v164
	v_add_f32_e32 v164, v63, v2
	v_and_b32_e32 v164, 0xffffff00, v164
	v_or_b32_e32 v164, 0x70, v164
	v_med3_f32 v163, v162, v163, v164
	v_med3_f32 v162, v161, v162, v164
	v_med3_f32 v161, v160, v161, v164
	v_med3_f32 v160, v159, v160, v164
	v_med3_f32 v159, v158, v159, v164
	v_med3_f32 v158, v157, v158, v164
	v_med3_f32 v157, v156, v157, v164
	v_med3_f32 v156, v155, v156, v164
	v_max_f32_e32 v155, v155, v164
	v_add_f32_e32 v164, v63, v4
	v_and_b32_e32 v164, 0xffffff00, v164
	v_or_b32_e32 v164, 0x71, v164
	v_max_f32_e32 v163, v163, v164
	v_add_f32_e32 v164, v67, v2
	v_and_b32_e32 v164, 0xffffff00, v164
	v_or_b32_e32 v164, 0x80, v164
	v_med3_f32 v163, v162, v163, v164
	v_med3_f32 v162, v161, v162, v164
	v_med3_f32 v161, v160, v161, v164
	v_med3_f32 v160, v159, v160, v164
	v_med3_f32 v159, v158, v159, v164
	v_med3_f32 v158, v157, v158, v164
	v_med3_f32 v157, v156, v157, v164
	v_max_f32_e32 v156, v156, v164
	v_add_f32_e32 v164, v59, v2
	v_and_b32_e32 v164, 0xffffff00, v164
	v_or_b32_e32 v164, 0x90, v164
	v_med3_f32 v163, v162, v163, v164
	v_med3_f32 v162, v161, v162, v164
	v_med3_f32 v161, v160, v161, v164
	v_med3_f32 v160, v159, v160, v164
	v_med3_f32 v159, v158, v159, v164
	v_med3_f32 v158, v157, v158, v164
	v_max_f32_e32 v157, v157, v164
	v_add_f32_e32 v164, v55, v2
	v_and_b32_e32 v164, 0xffffff00, v164
	v_or_b32_e32 v164, 0xa0, v164
	v_med3_f32 v163, v162, v163, v164
	v_med3_f32 v162, v161, v162, v164
	v_med3_f32 v161, v160, v161, v164
	v_med3_f32 v160, v159, v160, v164
	v_med3_f32 v159, v158, v159, v164
	v_max_f32_e32 v158, v158, v164
	v_add_f32_e32 v164, v47, v2
	v_and_b32_e32 v164, 0xffffff00, v164
	v_or_b32_e32 v164, 0xb0, v164
	v_med3_f32 v163, v162, v163, v164
	v_med3_f32 v162, v161, v162, v164
	v_med3_f32 v161, v160, v161, v164
	v_med3_f32 v160, v159, v160, v164
	v_max_f32_e32 v159, v159, v164
	v_add_f32_e32 v164, v51, v2
	v_and_b32_e32 v164, 0xffffff00, v164
	v_or_b32_e32 v164, 0xc0, v164
	v_med3_f32 v163, v162, v163, v164
	v_med3_f32 v162, v161, v162, v164
	v_med3_f32 v161, v160, v161, v164
	v_max_f32_e32 v160, v160, v164
	v_add_f32_e32 v164, v39, v2
	v_and_b32_e32 v164, 0xffffff00, v164
	v_or_b32_e32 v164, 0xd0, v164
	v_med3_f32 v163, v162, v163, v164
	v_med3_f32 v162, v161, v162, v164
	v_max_f32_e32 v161, v161, v164
	v_add_f32_e32 v164, v43, v2
	v_and_b32_e32 v164, 0xffffff00, v164
	v_or_b32_e32 v164, 0xe0, v164
	v_med3_f32 v163, v162, v163, v164
	v_max_f32_e32 v162, v162, v164
	v_add_f32_e32 v164, v0, v2
	v_and_b32_e32 v164, 0xffffff00, v164
	v_or_b32_e32 v164, 0xf0, v164
	v_max_f32_e32 v163, v163, v164
	s_lshl_b32 s18, s16, 3
	s_andn2_b32 s18, s18, 63
	v_add_u32_e32 v18, s18, v117
	s_movk_i32 s18, 0xff00
	v_sub_f32_e32 v5, v149, v148
	v_mul_f32_e32 v5, 0x3fb8aa3b, v5
	v_exp_f32_e32 v101, v5
	v_sub_f32_e32 v5, v150, v148
	v_mul_f32_e32 v5, 0x3fb8aa3b, v5
	v_exp_f32_e32 v104, v5
	v_sub_f32_e32 v5, v151, v148
	v_mul_f32_e32 v5, 0x3fb8aa3b, v5
	v_exp_f32_e32 v105, v5
	v_sub_f32_e32 v5, v152, v148
	v_mul_f32_e32 v5, 0x3fb8aa3b, v5
	v_exp_f32_e32 v102, v5
	v_sub_f32_e32 v5, v153, v148
	v_mul_f32_e32 v5, 0x3fb8aa3b, v5
	v_exp_f32_e32 v103, v5
	v_sub_f32_e32 v5, v154, v148
	v_mul_f32_e32 v5, 0x3fb8aa3b, v5
	v_exp_f32_e32 v110, v5
	v_sub_f32_e32 v5, v155, v148
	v_sub_f32_e32 v3, v148, v148
	v_mul_f32_e32 v5, 0x3fb8aa3b, v5
	v_mul_f32_e32 v3, 0x3fb8aa3b, v3
	v_exp_f32_e32 v111, v5
	v_sub_f32_e32 v5, v156, v148
	v_exp_f32_e32 v100, v3
	v_mul_f32_e32 v5, 0x3fb8aa3b, v5
	v_exp_f32_e32 v112, v5
	v_sub_f32_e32 v5, v157, v148
	v_mul_f32_e32 v5, 0x3fb8aa3b, v5
	v_exp_f32_e32 v113, v5
	v_sub_f32_e32 v5, v158, v148
	v_add_f32_e32 v3, 0, v100
	v_mul_f32_e32 v5, 0x3fb8aa3b, v5
	v_add_f32_e32 v3, v3, v101
	v_exp_f32_e32 v114, v5
	v_sub_f32_e32 v5, v159, v148
	v_add_f32_e32 v3, v3, v104
	v_mul_f32_e32 v5, 0x3fb8aa3b, v5
	v_add_f32_e32 v3, v3, v105
	v_exp_f32_e32 v115, v5
	v_sub_f32_e32 v5, v160, v148
	v_add_f32_e32 v3, v3, v102
	v_mul_f32_e32 v5, 0x3fb8aa3b, v5
	v_add_f32_e32 v3, v3, v103
	v_exp_f32_e32 v106, v5
	v_sub_f32_e32 v5, v161, v148
	v_add_f32_e32 v3, v3, v110
	v_mul_f32_e32 v5, 0x3fb8aa3b, v5
	v_add_f32_e32 v3, v3, v111
	v_exp_f32_e32 v107, v5
	v_sub_f32_e32 v5, v162, v148
	v_add_f32_e32 v3, v3, v112
	v_mul_f32_e32 v5, 0x3fb8aa3b, v5
	v_add_f32_e32 v3, v3, v113
	v_exp_f32_e32 v108, v5
	v_sub_f32_e32 v5, v163, v148
	v_add_f32_e32 v3, v3, v114
	v_mul_f32_e32 v5, 0x3fb8aa3b, v5
	v_add_f32_e32 v3, v3, v115
	v_exp_f32_e32 v109, v5
	v_add_f32_e32 v3, v3, v106
	v_add_f32_e32 v3, v3, v107
	v_add_f32_e32 v3, v3, v108
	v_add_f32_e32 v3, v3, v109
	v_div_scale_f32 v5, s[18:19], v3, v3, 1.0
	v_rcp_f32_e32 v6, v5
	v_ashrrev_i32_e32 v19, 31, v18
	s_lshl_b32 s52, s17, 6
	s_mov_b32 s17, 0x10000
	v_fma_f32 v17, -v5, v6, 1.0
	v_fmac_f32_e32 v6, v17, v6
	v_div_scale_f32 v17, vcc, 1.0, v3, 1.0
	v_mul_f32_e32 v20, v17, v6
	v_fma_f32 v21, -v5, v20, v17
	v_fmac_f32_e32 v20, v21, v6
	v_fma_f32 v5, -v5, v20, v17
	v_div_fmas_f32 v5, v5, v6, v20
	v_div_fixup_f32 v116, v5, v3, 1.0
	v_bfe_u32 v3, v163, 4, 4
	v_and_b32_e32 v2, 15, v163
	v_and_b32_e32 v17, 15, v155
	v_add_u32_e32 v3, v138, v3
	v_add_u32_e32 v2, v138, v2
	v_add_u32_e32 v17, v138, v17
	ds_read_u8 v3, v3
	ds_read_u8 v17, v17 offset:16
	ds_read_u8 v2, v2 offset:16
	v_and_b32_e32 v6, 15, v160
	v_add_u32_e32 v6, v138, v6
	ds_read_u8 v6, v6 offset:16
	v_lshlrev_b64 v[120:121], 9, v[18:19]
	s_waitcnt lgkmcnt(1)
; DEV void phase_peer_score(const Params& p, int layer, int M, char* smem) {
;     ...
;     int eid[16];
; #pragma unroll
;     for (int t = 0; t < 16; t++) {
;       unsigned code = __float_as_uint(R[t]) & 255u;
;       eid[t] = (int)tab[code >> 4] * 128 + (int)tab[16 + (code & 15u)];
;     }
	v_lshl_add_u32 v5, v3, 7, v2
	v_bfe_u32 v2, v162, 4, 4
	v_and_b32_e32 v3, 15, v162
	v_add_u32_e32 v2, v138, v2
	v_add_u32_e32 v3, v138, v3
	ds_read_u8 v2, v2
	ds_read_u8 v3, v3 offset:16
	v_lshl_add_u64 v[18:19], s[2:3], 0, v[120:121]
	v_lshl_add_u64 v[118:119], v[18:19], 0, s[52:53]
	v_lshl_add_u64 v[120:121], s[0:1], 0, v[120:121]
	v_lshl_add_u64 v[120:121], v[120:121], 0, s[52:53]
	s_waitcnt lgkmcnt(0)
	v_lshl_add_u32 v4, v2, 7, v3
	v_bfe_u32 v2, v161, 4, 4
	v_and_b32_e32 v3, 15, v161
	v_add_u32_e32 v2, v138, v2
	v_add_u32_e32 v3, v138, v3
	ds_read_u8 v2, v2
	ds_read_u8 v3, v3 offset:16
	v_and_b32_e32 v7, 15, v159
	v_add_u32_e32 v7, v138, v7
	ds_read_u8 v7, v7 offset:16
	s_waitcnt lgkmcnt(1)
	v_lshl_add_u32 v3, v2, 7, v3
	v_bfe_u32 v2, v160, 4, 4
	v_add_u32_e32 v2, v138, v2
	ds_read_u8 v2, v2
	s_waitcnt lgkmcnt(0)
	v_lshl_add_u32 v2, v2, 7, v6
	v_bfe_u32 v6, v159, 4, 4
	v_add_u32_e32 v6, v138, v6
	ds_read_u8 v6, v6
	s_waitcnt lgkmcnt(0)
	v_lshl_add_u32 v9, v6, 7, v7
	v_bfe_u32 v6, v158, 4, 4
	v_and_b32_e32 v7, 15, v158
	v_add_u32_e32 v6, v138, v6
	v_add_u32_e32 v7, v138, v7
	ds_read_u8 v6, v6
	ds_read_u8 v7, v7 offset:16
	s_waitcnt lgkmcnt(0)
	v_lshl_add_u32 v8, v6, 7, v7
	v_bfe_u32 v6, v157, 4, 4
	v_and_b32_e32 v7, 15, v157
	v_add_u32_e32 v6, v138, v6
	v_add_u32_e32 v7, v138, v7
	ds_read_u8 v6, v6
	ds_read_u8 v7, v7 offset:16
	s_waitcnt lgkmcnt(0)
	v_lshl_add_u32 v7, v6, 7, v7
	v_bfe_u32 v6, v156, 4, 4
	v_and_b32_e32 v13, 15, v156
	v_add_u32_e32 v6, v138, v6
	v_add_u32_e32 v13, v138, v13
	ds_read_u8 v6, v6
	ds_read_u8 v13, v13 offset:16
	s_waitcnt lgkmcnt(0)
	v_lshl_add_u32 v6, v6, 7, v13
	v_bfe_u32 v13, v155, 4, 4
	v_add_u32_e32 v13, v138, v13
	ds_read_u8 v13, v13
	s_waitcnt lgkmcnt(0)
	v_lshl_add_u32 v13, v13, 7, v17
	v_bfe_u32 v17, v154, 4, 4
	v_and_b32_e32 v12, 15, v154
	v_add_u32_e32 v17, v138, v17
	v_add_u32_e32 v12, v138, v12
	ds_read_u8 v17, v17
	ds_read_u8 v12, v12 offset:16
	s_waitcnt lgkmcnt(0)
	v_lshl_add_u32 v12, v17, 7, v12
	v_bfe_u32 v17, v153, 4, 4
	v_and_b32_e32 v11, 15, v153
	v_add_u32_e32 v17, v138, v17
	v_add_u32_e32 v11, v138, v11
	ds_read_u8 v17, v17
	ds_read_u8 v11, v11 offset:16
	s_waitcnt lgkmcnt(0)
	v_lshl_add_u32 v11, v17, 7, v11
	v_bfe_u32 v17, v152, 4, 4
	v_and_b32_e32 v10, 15, v152
	v_add_u32_e32 v17, v138, v17
	v_add_u32_e32 v10, v138, v10
	ds_read_u8 v17, v17
	ds_read_u8 v10, v10 offset:16
	s_waitcnt lgkmcnt(0)
	v_lshl_add_u32 v10, v17, 7, v10
	v_bfe_u32 v17, v151, 4, 4
	v_and_b32_e32 v16, 15, v151
	v_add_u32_e32 v17, v138, v17
	v_add_u32_e32 v16, v138, v16
	ds_read_u8 v17, v17
	ds_read_u8 v16, v16 offset:16
	s_waitcnt lgkmcnt(0)
	v_lshl_add_u32 v17, v17, 7, v16
	v_bfe_u32 v16, v150, 4, 4
	v_and_b32_e32 v15, 15, v150
	v_add_u32_e32 v16, v138, v16
	v_add_u32_e32 v15, v138, v15
	ds_read_u8 v16, v16
	ds_read_u8 v15, v15 offset:16
	s_waitcnt lgkmcnt(0)
	v_lshl_add_u32 v16, v16, 7, v15
	v_bfe_u32 v15, v149, 4, 4
	v_and_b32_e32 v14, 15, v149
	v_add_u32_e32 v15, v138, v15
	v_add_u32_e32 v14, v138, v14
	ds_read_u8 v15, v15
	ds_read_u8 v14, v14 offset:16
	s_waitcnt lgkmcnt(0)
	v_lshl_add_u32 v15, v15, 7, v14
	v_bfe_u32 v14, v148, 4, 4
	v_and_b32_e32 v0, 15, v148
	v_add_u32_e32 v14, v138, v14
	v_add_u32_e32 v0, v138, v0
	ds_read_u8 v14, v14
	ds_read_u8 v0, v0 offset:16
	s_waitcnt lgkmcnt(0)
; DEV void phase_peer_score(const Params& p, int layer, int M, char* smem) {
;     ...
;     if (quad == 0) {
;       int* eo = EIDX + (size_t)m * 128 + h * 16;
;       float* go = GATE + (size_t)m * 128 + h * 16;
;       float* uo = go + (size_t)MT * 128;
;       float us[16], vs[16];
; #pragma unroll
;       for (int t = 0; t < 16; t++) { us[t] = USC[eid[t]]; vs[t] = USC[16384 + eid[t]]; }
; #pragma unroll
;       for (int t = 0; t < 16; t += 4) {
;         *(int4*)(eo + t) = make_int4(eid[t], eid[t + 1], eid[t + 2], eid[t + 3]);
;         *(float4*)(go + t) = make_float4(ev[t] * inv * vs[t], ev[t + 1] * inv * vs[t + 1], ev[t + 2] * inv * vs[t + 2], ev[t + 3] * inv * vs[t + 3]);
;         *(float4*)(uo + t) = make_float4(us[t], us[t + 1], us[t + 2], us[t + 3]);
;       }
;     }
	v_lshl_add_u32 v14, v14, 7, v0
	v_lshlrev_b32_e32 v0, 2, v14
	v_lshl_add_u64 v[20:21], s[6:7], 0, v[0:1]
	v_add_co_u32_e32 v20, vcc, s17, v20
	global_load_dword v18, v0, s[6:7]
	s_nop 0
	v_addc_co_u32_e32 v21, vcc, 0, v21, vcc
	global_load_dword v122, v[20:21], off
	v_lshlrev_b32_e32 v0, 2, v15
	v_lshl_add_u64 v[20:21], s[6:7], 0, v[0:1]
	v_add_co_u32_e32 v20, vcc, s17, v20
	global_load_dword v19, v0, s[6:7]
	s_nop 0
	v_addc_co_u32_e32 v21, vcc, 0, v21, vcc
	global_load_dword v123, v[20:21], off
	v_lshlrev_b32_e32 v0, 2, v16
	v_lshl_add_u64 v[22:23], s[6:7], 0, v[0:1]
	v_add_co_u32_e32 v22, vcc, s17, v22
	global_load_dword v20, v0, s[6:7]
	s_nop 0
	v_addc_co_u32_e32 v23, vcc, 0, v23, vcc
	global_load_dword v126, v[22:23], off
	v_lshlrev_b32_e32 v0, 2, v17
	v_lshl_add_u64 v[22:23], s[6:7], 0, v[0:1]
	v_add_co_u32_e32 v22, vcc, s17, v22
	global_load_dword v21, v0, s[6:7]
	s_nop 0
	v_addc_co_u32_e32 v23, vcc, 0, v23, vcc
	global_load_dword v127, v[22:23], off
	v_lshlrev_b32_e32 v0, 2, v10
	v_lshl_add_u64 v[24:25], s[6:7], 0, v[0:1]
	v_add_co_u32_e32 v24, vcc, s17, v24
	global_load_dword v22, v0, s[6:7]
	s_nop 0
	v_addc_co_u32_e32 v25, vcc, 0, v25, vcc
	global_load_dword v124, v[24:25], off
	v_lshlrev_b32_e32 v0, 2, v11
	v_lshl_add_u64 v[24:25], s[6:7], 0, v[0:1]
	v_add_co_u32_e32 v24, vcc, s17, v24
	global_load_dword v23, v0, s[6:7]
	s_nop 0
	v_addc_co_u32_e32 v25, vcc, 0, v25, vcc
	global_load_dword v125, v[24:25], off
	v_lshlrev_b32_e32 v0, 2, v12
	v_lshl_add_u64 v[26:27], s[6:7], 0, v[0:1]
	v_add_co_u32_e32 v26, vcc, s17, v26
	global_load_dword v24, v0, s[6:7]
	s_nop 0
	v_addc_co_u32_e32 v27, vcc, 0, v27, vcc
	global_load_dword v128, v[26:27], off
	v_lshlrev_b32_e32 v0, 2, v13
	v_lshl_add_u64 v[26:27], s[6:7], 0, v[0:1]
	v_add_co_u32_e32 v26, vcc, s17, v26
	global_load_dword v25, v0, s[6:7]
	s_nop 0
	v_addc_co_u32_e32 v27, vcc, 0, v27, vcc
	global_load_dword v129, v[26:27], off
	v_lshlrev_b32_e32 v0, 2, v6
	v_lshl_add_u64 v[28:29], s[6:7], 0, v[0:1]
	v_add_co_u32_e32 v28, vcc, s17, v28
	global_load_dword v26, v0, s[6:7]
	s_nop 0
	v_addc_co_u32_e32 v29, vcc, 0, v29, vcc
	global_load_dword v130, v[28:29], off
	v_lshlrev_b32_e32 v0, 2, v7
	v_lshl_add_u64 v[28:29], s[6:7], 0, v[0:1]
	v_add_co_u32_e32 v28, vcc, s17, v28
	global_load_dword v27, v0, s[6:7]
	s_nop 0
	v_addc_co_u32_e32 v29, vcc, 0, v29, vcc
	global_load_dword v131, v[28:29], off
	v_lshlrev_b32_e32 v0, 2, v8
	v_lshl_add_u64 v[30:31], s[6:7], 0, v[0:1]
	v_add_co_u32_e32 v30, vcc, s17, v30
	global_load_dword v28, v0, s[6:7]
	s_nop 0
	v_addc_co_u32_e32 v31, vcc, 0, v31, vcc
	global_load_dword v132, v[30:31], off
	v_lshlrev_b32_e32 v0, 2, v9
	v_lshl_add_u64 v[30:31], s[6:7], 0, v[0:1]
	v_add_co_u32_e32 v30, vcc, s17, v30
	global_load_dword v29, v0, s[6:7]
	s_nop 0
	v_addc_co_u32_e32 v31, vcc, 0, v31, vcc
	global_load_dword v133, v[30:31], off
	v_lshlrev_b32_e32 v0, 2, v2
	v_lshl_add_u64 v[32:33], s[6:7], 0, v[0:1]
	v_add_co_u32_e32 v32, vcc, s17, v32
	global_load_dword v30, v0, s[6:7]
	s_nop 0
	v_addc_co_u32_e32 v33, vcc, 0, v33, vcc
	global_load_dword v134, v[32:33], off
	v_lshlrev_b32_e32 v0, 2, v3
	v_lshl_add_u64 v[32:33], s[6:7], 0, v[0:1]
	v_add_co_u32_e32 v32, vcc, s17, v32
	global_load_dword v31, v0, s[6:7]
	s_nop 0
	v_addc_co_u32_e32 v33, vcc, 0, v33, vcc
	global_load_dword v135, v[32:33], off
	v_lshlrev_b32_e32 v0, 2, v4
	v_lshl_add_u64 v[136:137], s[6:7], 0, v[0:1]
	v_add_co_u32_e32 v136, vcc, s17, v136
	global_load_dword v32, v0, s[6:7]
	s_nop 0
	v_addc_co_u32_e32 v137, vcc, 0, v137, vcc
	global_load_dword v136, v[136:137], off
	v_lshlrev_b32_e32 v0, 2, v5
	v_lshl_add_u64 v[140:141], s[6:7], 0, v[0:1]
	v_add_co_u32_e32 v140, vcc, s17, v140
	global_load_dword v33, v0, s[6:7]
	s_nop 0
	v_addc_co_u32_e32 v141, vcc, 0, v141, vcc
	global_load_dword v137, v[140:141], off
	s_mov_b32 s17, 0x840000
	global_store_dwordx4 v[120:121], v[14:17], off
	s_nop 1
	v_pk_mul_f32 v[14:15], v[100:101], v[116:117] op_sel_hi:[1,0]
	v_pk_mul_f32 v[16:17], v[104:105], v[116:117] op_sel_hi:[1,0]
	s_waitcnt vmcnt(29)
	v_pk_mul_f32 v[14:15], v[14:15], v[122:123]
	s_waitcnt vmcnt(25)
	v_pk_mul_f32 v[16:17], v[16:17], v[126:127]
	global_store_dwordx4 v[118:119], v[14:17], off
	s_nop 1
	v_add_co_u32_e32 v14, vcc, s17, v118
	s_nop 1
	v_addc_co_u32_e32 v15, vcc, 0, v119, vcc
	global_store_dwordx4 v[14:15], v[18:21], off
	global_store_dwordx4 v[120:121], v[10:13], off offset:16
	s_nop 1
	v_pk_mul_f32 v[10:11], v[102:103], v[116:117] op_sel_hi:[1,0]
	v_pk_mul_f32 v[12:13], v[110:111], v[116:117] op_sel_hi:[1,0]
	s_waitcnt vmcnt(24)
	v_pk_mul_f32 v[10:11], v[10:11], v[124:125]
	s_waitcnt vmcnt(20)
	v_pk_mul_f32 v[12:13], v[12:13], v[128:129]
	global_store_dwordx4 v[118:119], v[10:13], off offset:16
	global_store_dwordx4 v[14:15], v[22:25], off offset:16
	global_store_dwordx4 v[120:121], v[6:9], off offset:32
	s_nop 1
	v_pk_mul_f32 v[6:7], v[112:113], v[116:117] op_sel_hi:[1,0]
	v_pk_mul_f32 v[8:9], v[114:115], v[116:117] op_sel_hi:[1,0]
	s_waitcnt vmcnt(19)
	v_pk_mul_f32 v[6:7], v[6:7], v[130:131]
	s_waitcnt vmcnt(15)
	v_pk_mul_f32 v[8:9], v[8:9], v[132:133]
	global_store_dwordx4 v[118:119], v[6:9], off offset:32
	global_store_dwordx4 v[14:15], v[26:29], off offset:32
	global_store_dwordx4 v[120:121], v[2:5], off offset:48
	s_nop 1
	v_pk_mul_f32 v[2:3], v[106:107], v[116:117] op_sel_hi:[1,0]
	v_pk_mul_f32 v[4:5], v[108:109], v[116:117] op_sel_hi:[1,0]
	s_waitcnt vmcnt(14)
	v_pk_mul_f32 v[2:3], v[2:3], v[134:135]
	s_waitcnt vmcnt(10)
	v_pk_mul_f32 v[4:5], v[4:5], v[136:137]
	global_store_dwordx4 v[118:119], v[2:5], off offset:48
	global_store_dwordx4 v[14:15], v[30:33], off offset:48
	s_branch .LBB0_627
